# design F k-loop: s_setprio 1 over the odd (fill + prefetch) slice, LDS fills and loads clustered between MFMA groups of four and spread over all eight groups
# speedup vs baseline: 1.0967x; 1.0255x over previous
; template <int MODE>
; __device__ void gemm_tile2(const u16* __restrict__ X, int lda, const u16* __restrict__ W, int ldb, int K,
;                            int m0, int n0, u16* __restrict__ outb, int vbase,
;                            const float* resid, float* outf, unsigned char* smem) {
;     ...
;   G2_GLOAD(0, 0);
;   G2_GLOAD(1, 1);
;   __syncthreads();
;   G2_LSTORE(0, 0);
;   G2_GLOAD(0, 2);
;   __syncthreads();
;   for (int kt2 = 0; kt2 < nk; kt2 += 2) {
; #pragma unroll
;     for (int h = 0; h < 2; ++h) {
;       const int kt = kt2 + h;
;       const u16* st = sbase + h * G2STAGE;
;       bf16x8 fw[4], fx[4];
; #pragma unroll
;       for (int j = 0; j < 4; ++j) fw[j] = *(const bf16x8*)(st + 256 * G2S + (ww * 64 + j * 16 + l15) * G2S + fsw);
; #pragma unroll
;       for (int i = 0; i < 4; ++i) fx[i] = *(const bf16x8*)(st + (wx * 128 + i * 16 + l15) * G2S + fsw);
;       __builtin_amdgcn_sched_barrier(0);
;       __builtin_amdgcn_s_setprio(1);
; #pragma unroll
;       for (int i = 0; i < 4; ++i) {
; #pragma unroll
;         for (int j = 0; j < 4; ++j) {
;           if (MODE == 1) acc[i][j] = mfma16(fx[i], fw[j], acc[i][j]);
;           else acc[i][j] = mfma16(fw[j], fx[i], acc[i][j]);
;         }
;       }
;       __builtin_amdgcn_s_setprio(0);
;       __builtin_amdgcn_sched_barrier(0);
; #pragma unroll
;       for (int i = 0; i < 4; ++i) fx[i] = *(const bf16x8*)(st + (wx * 128 + (i + 4) * 16 + l15) * G2S + fsw);
;       __builtin_amdgcn_sched_barrier(0);
;       if (kt + 1 < nk) G2_LSTORE(1 - h, 1 - h);
;       if (kt + 3 < nk) G2_GLOAD(1 - h, kt + 3);
;       __builtin_amdgcn_sched_barrier(0);
;       __builtin_amdgcn_s_setprio(1);
; #pragma unroll
;       for (int i = 0; i < 4; ++i) {
; #pragma unroll
;         for (int j = 0; j < 4; ++j) {
;           if (MODE == 1) acc[i + 4][j] = mfma16(fx[i], fw[j], acc[i + 4][j]);
;           else acc[i + 4][j] = mfma16(fw[j], fx[i], acc[i + 4][j]);
;         }
;       }
;       __builtin_amdgcn_s_setprio(0);
;       __syncthreads();
;     }
.Lf0_loop:
	s_waitcnt lgkmcnt(3)
	v_mfma_f32_16x16x32_bf16 v[174:177], v[178:181], v[194:197], v[174:177]
	v_mfma_f32_16x16x32_bf16 v[170:173], v[182:185], v[194:197], v[170:173]
	v_mfma_f32_16x16x32_bf16 v[166:169], v[186:189], v[194:197], v[166:169]
	v_mfma_f32_16x16x32_bf16 v[162:165], v[190:193], v[194:197], v[162:165]
	ds_read_b128 v[194:197], v236 offset:4096
	ds_read_b128 v[238:241], v232 offset:16384
	s_waitcnt lgkmcnt(4)
	v_mfma_f32_16x16x32_bf16 v[158:161], v[178:181], v[198:201], v[158:161]
	v_mfma_f32_16x16x32_bf16 v[154:157], v[182:185], v[198:201], v[154:157]
	v_mfma_f32_16x16x32_bf16 v[150:153], v[186:189], v[198:201], v[150:153]
	v_mfma_f32_16x16x32_bf16 v[146:149], v[190:193], v[198:201], v[146:149]
	ds_read_b128 v[198:201], v236 offset:5120
	ds_read_b128 v[242:245], v232 offset:17408
	s_waitcnt lgkmcnt(5)
	v_mfma_f32_16x16x32_bf16 v[142:145], v[178:181], v[202:205], v[142:145]
	v_mfma_f32_16x16x32_bf16 v[138:141], v[182:185], v[202:205], v[138:141]
	v_mfma_f32_16x16x32_bf16 v[134:137], v[186:189], v[202:205], v[134:137]
	v_mfma_f32_16x16x32_bf16 v[130:133], v[190:193], v[202:205], v[130:133]
	ds_read_b128 v[202:205], v236 offset:6144
	ds_read_b128 v[246:249], v232 offset:18432
	s_waitcnt lgkmcnt(6)
	v_mfma_f32_16x16x32_bf16 v[126:129], v[178:181], v[206:209], v[126:129]
	v_mfma_f32_16x16x32_bf16 v[122:125], v[182:185], v[206:209], v[122:125]
	v_mfma_f32_16x16x32_bf16 v[118:121], v[186:189], v[206:209], v[118:121]
	v_mfma_f32_16x16x32_bf16 v[114:117], v[190:193], v[206:209], v[114:117]
	ds_read_b128 v[206:209], v236 offset:7168
	ds_read_b128 v[222:225], v232 offset:19456
	s_sub_i32 s38, s35, s6
	v_add_u32_e32 v235, s38, v235
	v_add_u32_e32 v236, s38, v236
	s_waitcnt lgkmcnt(7)
	v_mfma_f32_16x16x32_bf16 v[110:113], v[178:181], v[194:197], v[110:113]
	v_mfma_f32_16x16x32_bf16 v[106:109], v[182:185], v[194:197], v[106:109]
	v_mfma_f32_16x16x32_bf16 v[102:105], v[186:189], v[194:197], v[102:105]
	v_mfma_f32_16x16x32_bf16 v[98:101], v[190:193], v[194:197], v[98:101]
	ds_read_b128 v[194:197], v237
	s_waitcnt lgkmcnt(6)
	v_mfma_f32_16x16x32_bf16 v[94:97], v[178:181], v[198:201], v[94:97]
	v_mfma_f32_16x16x32_bf16 v[90:93], v[182:185], v[198:201], v[90:93]
	v_mfma_f32_16x16x32_bf16 v[86:89], v[186:189], v[198:201], v[86:89]
	v_mfma_f32_16x16x32_bf16 v[82:85], v[190:193], v[198:201], v[82:85]
	ds_read_b128 v[198:201], v237 offset:1024
	s_waitcnt lgkmcnt(5)
	v_mfma_f32_16x16x32_bf16 v[78:81], v[178:181], v[202:205], v[78:81]
	v_mfma_f32_16x16x32_bf16 v[74:77], v[182:185], v[202:205], v[74:77]
	v_mfma_f32_16x16x32_bf16 v[70:73], v[186:189], v[202:205], v[70:73]
	v_mfma_f32_16x16x32_bf16 v[66:69], v[190:193], v[202:205], v[66:69]
	ds_read_b128 v[202:205], v237 offset:2048
	s_waitcnt lgkmcnt(4)
	v_mfma_f32_16x16x32_bf16 v[62:65], v[178:181], v[206:209], v[62:65]
	v_mfma_f32_16x16x32_bf16 v[58:61], v[182:185], v[206:209], v[58:61]
	v_mfma_f32_16x16x32_bf16 v[54:57], v[186:189], v[206:209], v[54:57]
	v_mfma_f32_16x16x32_bf16 v[50:53], v[190:193], v[206:209], v[50:53]
	ds_read_b128 v[206:209], v237 offset:3072
	s_sub_i32 s38, s6, s35
	v_mad_i32_i24 v234, v221, s38, v220
	v_add_u32_e32 v234, s35, v234
	s_barrier
	s_setprio 1
	s_waitcnt lgkmcnt(3)
	v_mfma_f32_16x16x32_bf16 v[174:177], v[238:241], v[194:197], v[174:177]
	v_mfma_f32_16x16x32_bf16 v[170:173], v[242:245], v[194:197], v[170:173]
	v_mfma_f32_16x16x32_bf16 v[166:169], v[246:249], v[194:197], v[166:169]
	v_mfma_f32_16x16x32_bf16 v[162:165], v[222:225], v[194:197], v[162:165]
	ds_read_b128 v[194:197], v237 offset:4096
	s_waitcnt vmcnt(11)
	ds_write_b128 v234, v[2:5]
	s_waitcnt vmcnt(10)
	ds_write_b128 v234, v[6:9] offset:2048
	buffer_load_dwordx4 v[2:5], v218, s[24:27], 0 offen
	buffer_load_dwordx4 v[6:9], v219, s[24:27], 0 offen
	s_waitcnt lgkmcnt(5)
	v_mfma_f32_16x16x32_bf16 v[158:161], v[238:241], v[198:201], v[158:161]
	v_mfma_f32_16x16x32_bf16 v[154:157], v[242:245], v[198:201], v[154:157]
	v_mfma_f32_16x16x32_bf16 v[150:153], v[246:249], v[198:201], v[150:153]
	v_mfma_f32_16x16x32_bf16 v[146:149], v[222:225], v[198:201], v[146:149]
	ds_read_b128 v[198:201], v237 offset:5120
	s_waitcnt vmcnt(11)
	ds_write_b128 v234, v[10:13] offset:4096
	buffer_load_dwordx4 v[10:13], v218, s[24:27], s27 offen
	s_waitcnt lgkmcnt(6)
	v_mfma_f32_16x16x32_bf16 v[142:145], v[238:241], v[202:205], v[142:145]
	v_mfma_f32_16x16x32_bf16 v[138:141], v[242:245], v[202:205], v[138:141]
	v_mfma_f32_16x16x32_bf16 v[134:137], v[246:249], v[202:205], v[134:137]
	v_mfma_f32_16x16x32_bf16 v[130:133], v[222:225], v[202:205], v[130:133]
	ds_read_b128 v[202:205], v237 offset:6144
	s_waitcnt vmcnt(11)
	ds_write_b128 v234, v[14:17] offset:6144
	s_waitcnt vmcnt(10)
	ds_write_b128 v234, v[18:21] offset:8192
	buffer_load_dwordx4 v[14:17], v219, s[24:27], s27 offen
	buffer_load_dwordx4 v[18:21], v218, s[24:27], s77 offen
	s_waitcnt lgkmcnt(8)
	v_mfma_f32_16x16x32_bf16 v[126:129], v[238:241], v[206:209], v[126:129]
	v_mfma_f32_16x16x32_bf16 v[122:125], v[242:245], v[206:209], v[122:125]
	v_mfma_f32_16x16x32_bf16 v[118:121], v[246:249], v[206:209], v[118:121]
	v_mfma_f32_16x16x32_bf16 v[114:117], v[222:225], v[206:209], v[114:117]
	ds_read_b128 v[206:209], v237 offset:7168
	s_sub_i32 s38, s6, s7
	v_add_u32_e32 v232, s38, v232
	v_add_u32_e32 v237, s38, v237
	s_waitcnt vmcnt(11)
	ds_write_b128 v234, v[22:25] offset:10240
	buffer_load_dwordx4 v[22:25], v219, s[24:27], s77 offen
	s_waitcnt lgkmcnt(9)
	v_mfma_f32_16x16x32_bf16 v[110:113], v[238:241], v[194:197], v[110:113]
	v_mfma_f32_16x16x32_bf16 v[106:109], v[242:245], v[194:197], v[106:109]
	v_mfma_f32_16x16x32_bf16 v[102:105], v[246:249], v[194:197], v[102:105]
	v_mfma_f32_16x16x32_bf16 v[98:101], v[222:225], v[194:197], v[98:101]
	s_waitcnt vmcnt(11)
; template <int MODE>
; __device__ void gemm_tile2(const u16* __restrict__ X, int lda, const u16* __restrict__ W, int ldb, int K,
;                            int m0, int n0, u16* __restrict__ outb, int vbase,
;                            const float* resid, float* outf, unsigned char* smem) {
;     ...
;   G2_GLOAD(0, 0);
;   G2_GLOAD(1, 1);
;   __syncthreads();
;   G2_LSTORE(0, 0);
;   G2_GLOAD(0, 2);
;   __syncthreads();
;   for (int kt2 = 0; kt2 < nk; kt2 += 2) {
; #pragma unroll
;     for (int h = 0; h < 2; ++h) {
;       const int kt = kt2 + h;
;       const u16* st = sbase + h * G2STAGE;
;       bf16x8 fw[4], fx[4];
; #pragma unroll
;       for (int j = 0; j < 4; ++j) fw[j] = *(const bf16x8*)(st + 256 * G2S + (ww * 64 + j * 16 + l15) * G2S + fsw);
; #pragma unroll
;       for (int i = 0; i < 4; ++i) fx[i] = *(const bf16x8*)(st + (wx * 128 + i * 16 + l15) * G2S + fsw);
;       __builtin_amdgcn_sched_barrier(0);
;       __builtin_amdgcn_s_setprio(1);
; #pragma unroll
;       for (int i = 0; i < 4; ++i) {
; #pragma unroll
;         for (int j = 0; j < 4; ++j) {
;           if (MODE == 1) acc[i][j] = mfma16(fx[i], fw[j], acc[i][j]);
;           else acc[i][j] = mfma16(fw[j], fx[i], acc[i][j]);
;         }
;       }
;       __builtin_amdgcn_s_setprio(0);
;       __builtin_amdgcn_sched_barrier(0);
; #pragma unroll
;       for (int i = 0; i < 4; ++i) fx[i] = *(const bf16x8*)(st + (wx * 128 + (i + 4) * 16 + l15) * G2S + fsw);
;       __builtin_amdgcn_sched_barrier(0);
;       if (kt + 1 < nk) G2_LSTORE(1 - h, 1 - h);
;       if (kt + 3 < nk) G2_GLOAD(1 - h, kt + 3);
;       __builtin_amdgcn_sched_barrier(0);
;       __builtin_amdgcn_s_setprio(1);
; #pragma unroll
;       for (int i = 0; i < 4; ++i) {
; #pragma unroll
;         for (int j = 0; j < 4; ++j) {
;           if (MODE == 1) acc[i + 4][j] = mfma16(fx[i], fw[j], acc[i + 4][j]);
;           else acc[i + 4][j] = mfma16(fw[j], fx[i], acc[i + 4][j]);
;         }
;       }
;       __builtin_amdgcn_s_setprio(0);
;       __syncthreads();
;     }
	ds_write_b128 v234, v[26:29] offset:12288
	s_waitcnt vmcnt(10)
	ds_write_b128 v234, v[30:33] offset:14336
	buffer_load_dwordx4 v[26:29], v218, s[24:27], s78 offen
	buffer_load_dwordx4 v[30:33], v219, s[24:27], s78 offen
	s_waitcnt lgkmcnt(8)
	v_mfma_f32_16x16x32_bf16 v[94:97], v[238:241], v[198:201], v[94:97]
	v_mfma_f32_16x16x32_bf16 v[90:93], v[242:245], v[198:201], v[90:93]
	v_mfma_f32_16x16x32_bf16 v[86:89], v[246:249], v[198:201], v[86:89]
	v_mfma_f32_16x16x32_bf16 v[82:85], v[222:225], v[198:201], v[82:85]
	s_waitcnt vmcnt(11)
	ds_write_b128 v234, v[34:37] offset:16384
	buffer_load_dwordx4 v[34:37], v218, s[40:43], 0 offen
	s_waitcnt lgkmcnt(7)
	v_mfma_f32_16x16x32_bf16 v[78:81], v[238:241], v[202:205], v[78:81]
	v_mfma_f32_16x16x32_bf16 v[74:77], v[242:245], v[202:205], v[74:77]
	v_mfma_f32_16x16x32_bf16 v[70:73], v[246:249], v[202:205], v[70:73]
	v_mfma_f32_16x16x32_bf16 v[66:69], v[222:225], v[202:205], v[66:69]
	s_waitcnt vmcnt(11)
	ds_write_b128 v234, v[38:41] offset:18432
	s_waitcnt vmcnt(10)
	ds_write_b128 v234, v[42:45] offset:20480
	buffer_load_dwordx4 v[38:41], v219, s[40:43], 0 offen
	buffer_load_dwordx4 v[42:45], v218, s[40:43], s27 offen
	s_waitcnt lgkmcnt(6)
	v_mfma_f32_16x16x32_bf16 v[62:65], v[238:241], v[206:209], v[62:65]
	v_mfma_f32_16x16x32_bf16 v[58:61], v[242:245], v[206:209], v[58:61]
	v_mfma_f32_16x16x32_bf16 v[54:57], v[246:249], v[206:209], v[54:57]
	v_mfma_f32_16x16x32_bf16 v[50:53], v[222:225], v[206:209], v[50:53]
	s_waitcnt vmcnt(11)
	ds_write_b128 v234, v[46:49] offset:22528
	buffer_load_dwordx4 v[46:49], v219, s[40:43], s27 offen
	v_add_u32_e32 v218, 0x80, v218
	v_add_u32_e32 v219, 0x80, v219
	s_waitcnt lgkmcnt(0)
	s_setprio 0
	s_barrier
	s_mov_b32 s38, s35
	s_mov_b32 s35, s7
	s_mov_b32 s7, s6
	s_mov_b32 s6, s38
	ds_read_b128 v[178:181], v235 offset:16384
	ds_read_b128 v[182:185], v235 offset:17408
	ds_read_b128 v[186:189], v235 offset:18432
	ds_read_b128 v[190:193], v235 offset:19456
	ds_read_b128 v[194:197], v236
	ds_read_b128 v[198:201], v236 offset:1024
	ds_read_b128 v[202:205], v236 offset:2048
	ds_read_b128 v[206:209], v236 offset:3072
	s_add_u32 s1, s1, 1
	s_cmp_lt_u32 s1, 14
	s_cbranch_scc1 .Lf0_loop
	s_waitcnt lgkmcnt(3)
	v_mfma_f32_16x16x32_bf16 v[174:177], v[178:181], v[194:197], v[174:177]
	v_mfma_f32_16x16x32_bf16 v[170:173], v[182:185], v[194:197], v[170:173]
	v_mfma_f32_16x16x32_bf16 v[166:169], v[186:189], v[194:197], v[166:169]
	v_mfma_f32_16x16x32_bf16 v[162:165], v[190:193], v[194:197], v[162:165]
	ds_read_b128 v[194:197], v236 offset:4096
	ds_read_b128 v[238:241], v232 offset:16384
	s_waitcnt lgkmcnt(4)
	v_mfma_f32_16x16x32_bf16 v[158:161], v[178:181], v[198:201], v[158:161]
	v_mfma_f32_16x16x32_bf16 v[154:157], v[182:185], v[198:201], v[154:157]
	v_mfma_f32_16x16x32_bf16 v[150:153], v[186:189], v[198:201], v[150:153]
	v_mfma_f32_16x16x32_bf16 v[146:149], v[190:193], v[198:201], v[146:149]
	ds_read_b128 v[198:201], v236 offset:5120
	ds_read_b128 v[242:245], v232 offset:17408
	s_waitcnt lgkmcnt(5)
	v_mfma_f32_16x16x32_bf16 v[142:145], v[178:181], v[202:205], v[142:145]
	v_mfma_f32_16x16x32_bf16 v[138:141], v[182:185], v[202:205], v[138:141]
	v_mfma_f32_16x16x32_bf16 v[134:137], v[186:189], v[202:205], v[134:137]
	v_mfma_f32_16x16x32_bf16 v[130:133], v[190:193], v[202:205], v[130:133]
	ds_read_b128 v[202:205], v236 offset:6144
	ds_read_b128 v[246:249], v232 offset:18432
	s_waitcnt lgkmcnt(6)
	v_mfma_f32_16x16x32_bf16 v[126:129], v[178:181], v[206:209], v[126:129]
	v_mfma_f32_16x16x32_bf16 v[122:125], v[182:185], v[206:209], v[122:125]
	v_mfma_f32_16x16x32_bf16 v[118:121], v[186:189], v[206:209], v[118:121]
	v_mfma_f32_16x16x32_bf16 v[114:117], v[190:193], v[206:209], v[114:117]
	ds_read_b128 v[206:209], v236 offset:7168
	ds_read_b128 v[222:225], v232 offset:19456
	s_sub_i32 s38, s35, s6
	v_add_u32_e32 v235, s38, v235
	v_add_u32_e32 v236, s38, v236
	s_waitcnt lgkmcnt(7)
	v_mfma_f32_16x16x32_bf16 v[110:113], v[178:181], v[194:197], v[110:113]
	v_mfma_f32_16x16x32_bf16 v[106:109], v[182:185], v[194:197], v[106:109]
	v_mfma_f32_16x16x32_bf16 v[102:105], v[186:189], v[194:197], v[102:105]
	v_mfma_f32_16x16x32_bf16 v[98:101], v[190:193], v[194:197], v[98:101]
	ds_read_b128 v[194:197], v237
	s_waitcnt lgkmcnt(6)
	v_mfma_f32_16x16x32_bf16 v[94:97], v[178:181], v[198:201], v[94:97]
	v_mfma_f32_16x16x32_bf16 v[90:93], v[182:185], v[198:201], v[90:93]
	v_mfma_f32_16x16x32_bf16 v[86:89], v[186:189], v[198:201], v[86:89]
	v_mfma_f32_16x16x32_bf16 v[82:85], v[190:193], v[198:201], v[82:85]
	ds_read_b128 v[198:201], v237 offset:1024
	s_waitcnt lgkmcnt(5)
	v_mfma_f32_16x16x32_bf16 v[78:81], v[178:181], v[202:205], v[78:81]
	v_mfma_f32_16x16x32_bf16 v[74:77], v[182:185], v[202:205], v[74:77]
	v_mfma_f32_16x16x32_bf16 v[70:73], v[186:189], v[202:205], v[70:73]
	v_mfma_f32_16x16x32_bf16 v[66:69], v[190:193], v[202:205], v[66:69]
	ds_read_b128 v[202:205], v237 offset:2048
	s_waitcnt lgkmcnt(4)
	v_mfma_f32_16x16x32_bf16 v[62:65], v[178:181], v[206:209], v[62:65]
	v_mfma_f32_16x16x32_bf16 v[58:61], v[182:185], v[206:209], v[58:61]
	v_mfma_f32_16x16x32_bf16 v[54:57], v[186:189], v[206:209], v[54:57]
	v_mfma_f32_16x16x32_bf16 v[50:53], v[190:193], v[206:209], v[50:53]
	ds_read_b128 v[206:209], v237 offset:3072
	s_sub_i32 s38, s6, s35
	v_mad_i32_i24 v234, v221, s38, v220
	v_add_u32_e32 v234, s35, v234
	s_barrier
; template <int MODE>
; __device__ void gemm_tile2(const u16* __restrict__ X, int lda, const u16* __restrict__ W, int ldb, int K,
;                            int m0, int n0, u16* __restrict__ outb, int vbase,
;                            const float* resid, float* outf, unsigned char* smem) {
;     ...
; #pragma unroll
;       for (int i = 0; i < 4; ++i) fx[i] = *(const bf16x8*)(st + (wx * 128 + (i + 4) * 16 + l15) * G2S + fsw);
;       __builtin_amdgcn_sched_barrier(0);
;       if (kt + 1 < nk) G2_LSTORE(1 - h, 1 - h);
;       if (kt + 3 < nk) G2_GLOAD(1 - h, kt + 3);
;       __builtin_amdgcn_sched_barrier(0);
;       __builtin_amdgcn_s_setprio(1);
; #pragma unroll
;       for (int i = 0; i < 4; ++i) {
; #pragma unroll
;         for (int j = 0; j < 4; ++j) {
;           if (MODE == 1) acc[i + 4][j] = mfma16(fx[i], fw[j], acc[i + 4][j]);
;           else acc[i + 4][j] = mfma16(fw[j], fx[i], acc[i + 4][j]);
;         }
;       }
;       __builtin_amdgcn_s_setprio(0);
;       __syncthreads();
	s_setprio 1
	s_waitcnt lgkmcnt(3)
	v_mfma_f32_16x16x32_bf16 v[174:177], v[238:241], v[194:197], v[174:177]
	v_mfma_f32_16x16x32_bf16 v[170:173], v[242:245], v[194:197], v[170:173]
	v_mfma_f32_16x16x32_bf16 v[166:169], v[246:249], v[194:197], v[166:169]
	v_mfma_f32_16x16x32_bf16 v[162:165], v[222:225], v[194:197], v[162:165]
	ds_read_b128 v[194:197], v237 offset:4096
	s_waitcnt vmcnt(11)
	ds_write_b128 v234, v[2:5]
	s_waitcnt vmcnt(10)
	ds_write_b128 v234, v[6:9] offset:2048
	s_waitcnt lgkmcnt(5)
	v_mfma_f32_16x16x32_bf16 v[158:161], v[238:241], v[198:201], v[158:161]
	v_mfma_f32_16x16x32_bf16 v[154:157], v[242:245], v[198:201], v[154:157]
	v_mfma_f32_16x16x32_bf16 v[150:153], v[246:249], v[198:201], v[150:153]
	v_mfma_f32_16x16x32_bf16 v[146:149], v[222:225], v[198:201], v[146:149]
	ds_read_b128 v[198:201], v237 offset:5120
	s_waitcnt vmcnt(9)
	ds_write_b128 v234, v[10:13] offset:4096
	s_waitcnt lgkmcnt(6)
	v_mfma_f32_16x16x32_bf16 v[142:145], v[238:241], v[202:205], v[142:145]
	v_mfma_f32_16x16x32_bf16 v[138:141], v[242:245], v[202:205], v[138:141]
	v_mfma_f32_16x16x32_bf16 v[134:137], v[246:249], v[202:205], v[134:137]
	v_mfma_f32_16x16x32_bf16 v[130:133], v[222:225], v[202:205], v[130:133]
	ds_read_b128 v[202:205], v237 offset:6144
	s_waitcnt vmcnt(8)
	ds_write_b128 v234, v[14:17] offset:6144
	s_waitcnt vmcnt(7)
	ds_write_b128 v234, v[18:21] offset:8192
	s_waitcnt lgkmcnt(8)
	v_mfma_f32_16x16x32_bf16 v[126:129], v[238:241], v[206:209], v[126:129]
	v_mfma_f32_16x16x32_bf16 v[122:125], v[242:245], v[206:209], v[122:125]
	v_mfma_f32_16x16x32_bf16 v[118:121], v[246:249], v[206:209], v[118:121]
	v_mfma_f32_16x16x32_bf16 v[114:117], v[222:225], v[206:209], v[114:117]
	ds_read_b128 v[206:209], v237 offset:7168
	s_sub_i32 s38, s6, s7
	v_add_u32_e32 v232, s38, v232
	v_add_u32_e32 v237, s38, v237
	s_waitcnt vmcnt(6)
	ds_write_b128 v234, v[22:25] offset:10240
	s_waitcnt lgkmcnt(9)
	v_mfma_f32_16x16x32_bf16 v[110:113], v[238:241], v[194:197], v[110:113]
	v_mfma_f32_16x16x32_bf16 v[106:109], v[242:245], v[194:197], v[106:109]
	v_mfma_f32_16x16x32_bf16 v[102:105], v[246:249], v[194:197], v[102:105]
	v_mfma_f32_16x16x32_bf16 v[98:101], v[222:225], v[194:197], v[98:101]
	s_waitcnt vmcnt(5)
	ds_write_b128 v234, v[26:29] offset:12288
	s_waitcnt vmcnt(4)
	ds_write_b128 v234, v[30:33] offset:14336
	s_waitcnt lgkmcnt(8)
	v_mfma_f32_16x16x32_bf16 v[94:97], v[238:241], v[198:201], v[94:97]
	v_mfma_f32_16x16x32_bf16 v[90:93], v[242:245], v[198:201], v[90:93]
	v_mfma_f32_16x16x32_bf16 v[86:89], v[246:249], v[198:201], v[86:89]
	v_mfma_f32_16x16x32_bf16 v[82:85], v[222:225], v[198:201], v[82:85]
	s_waitcnt vmcnt(3)
	ds_write_b128 v234, v[34:37] offset:16384
	s_waitcnt lgkmcnt(7)
	v_mfma_f32_16x16x32_bf16 v[78:81], v[238:241], v[202:205], v[78:81]
	v_mfma_f32_16x16x32_bf16 v[74:77], v[242:245], v[202:205], v[74:77]
	v_mfma_f32_16x16x32_bf16 v[70:73], v[246:249], v[202:205], v[70:73]
	v_mfma_f32_16x16x32_bf16 v[66:69], v[222:225], v[202:205], v[66:69]
	s_waitcnt vmcnt(2)
	ds_write_b128 v234, v[38:41] offset:18432
	s_waitcnt vmcnt(1)
	ds_write_b128 v234, v[42:45] offset:20480
	s_waitcnt lgkmcnt(6)
	v_mfma_f32_16x16x32_bf16 v[62:65], v[238:241], v[206:209], v[62:65]
	v_mfma_f32_16x16x32_bf16 v[58:61], v[242:245], v[206:209], v[58:61]
	v_mfma_f32_16x16x32_bf16 v[54:57], v[246:249], v[206:209], v[54:57]
	v_mfma_f32_16x16x32_bf16 v[50:53], v[222:225], v[206:209], v[50:53]
	s_waitcnt vmcnt(0)
	ds_write_b128 v234, v[46:49] offset:22528
	s_waitcnt lgkmcnt(0)
	s_setprio 0
	s_barrier
; template <int MODE>
; __device__ void gemm_tile2(const u16* __restrict__ X, int lda, const u16* __restrict__ W, int ldb, int K,
;                            int m0, int n0, u16* __restrict__ outb, int vbase,
;                            const float* resid, float* outf, unsigned char* smem) {
;     ...
;   for (int kt2 = 0; kt2 < nk; kt2 += 2) {
; #pragma unroll
;     for (int h = 0; h < 2; ++h) {
;       const int kt = kt2 + h;
;       const u16* st = sbase + h * G2STAGE;
;       bf16x8 fw[4], fx[4];
; #pragma unroll
;       for (int j = 0; j < 4; ++j) fw[j] = *(const bf16x8*)(st + 256 * G2S + (ww * 64 + j * 16 + l15) * G2S + fsw);
; #pragma unroll
;       for (int i = 0; i < 4; ++i) fx[i] = *(const bf16x8*)(st + (wx * 128 + i * 16 + l15) * G2S + fsw);
;       __builtin_amdgcn_sched_barrier(0);
;       __builtin_amdgcn_s_setprio(1);
; #pragma unroll
;       for (int i = 0; i < 4; ++i) {
; #pragma unroll
;         for (int j = 0; j < 4; ++j) {
;           if (MODE == 1) acc[i][j] = mfma16(fx[i], fw[j], acc[i][j]);
;           else acc[i][j] = mfma16(fw[j], fx[i], acc[i][j]);
;         }
;       }
;       __builtin_amdgcn_s_setprio(0);
;       __builtin_amdgcn_sched_barrier(0);
; #pragma unroll
;       for (int i = 0; i < 4; ++i) fx[i] = *(const bf16x8*)(st + (wx * 128 + (i + 4) * 16 + l15) * G2S + fsw);
;       __builtin_amdgcn_sched_barrier(0);
;       if (kt + 1 < nk) G2_LSTORE(1 - h, 1 - h);
;       if (kt + 3 < nk) G2_GLOAD(1 - h, kt + 3);
;       __builtin_amdgcn_sched_barrier(0);
;       __builtin_amdgcn_s_setprio(1);
; #pragma unroll
;       for (int i = 0; i < 4; ++i) {
; #pragma unroll
;         for (int j = 0; j < 4; ++j) {
;           if (MODE == 1) acc[i + 4][j] = mfma16(fx[i], fw[j], acc[i + 4][j]);
;           else acc[i + 4][j] = mfma16(fw[j], fx[i], acc[i + 4][j]);
;         }
;       }
;       __builtin_amdgcn_s_setprio(0);
;       __syncthreads();
;     }
;   }
	s_mov_b32 s38, s35
	s_mov_b32 s35, s7
	s_mov_b32 s7, s6
	s_mov_b32 s6, s38
	ds_read_b128 v[178:181], v235 offset:16384
	ds_read_b128 v[182:185], v235 offset:17408
	ds_read_b128 v[186:189], v235 offset:18432
	ds_read_b128 v[190:193], v235 offset:19456
	ds_read_b128 v[194:197], v236
	ds_read_b128 v[198:201], v236 offset:1024
	ds_read_b128 v[202:205], v236 offset:2048
	ds_read_b128 v[206:209], v236 offset:3072
	s_waitcnt lgkmcnt(3)
	v_mfma_f32_16x16x32_bf16 v[174:177], v[178:181], v[194:197], v[174:177]
	v_mfma_f32_16x16x32_bf16 v[170:173], v[182:185], v[194:197], v[170:173]
	v_mfma_f32_16x16x32_bf16 v[166:169], v[186:189], v[194:197], v[166:169]
	v_mfma_f32_16x16x32_bf16 v[162:165], v[190:193], v[194:197], v[162:165]
	ds_read_b128 v[194:197], v236 offset:4096
	ds_read_b128 v[238:241], v232 offset:16384
	s_waitcnt lgkmcnt(4)
	v_mfma_f32_16x16x32_bf16 v[158:161], v[178:181], v[198:201], v[158:161]
	v_mfma_f32_16x16x32_bf16 v[154:157], v[182:185], v[198:201], v[154:157]
	v_mfma_f32_16x16x32_bf16 v[150:153], v[186:189], v[198:201], v[150:153]
	v_mfma_f32_16x16x32_bf16 v[146:149], v[190:193], v[198:201], v[146:149]
	ds_read_b128 v[198:201], v236 offset:5120
	ds_read_b128 v[242:245], v232 offset:17408
	s_waitcnt lgkmcnt(5)
	v_mfma_f32_16x16x32_bf16 v[142:145], v[178:181], v[202:205], v[142:145]
	v_mfma_f32_16x16x32_bf16 v[138:141], v[182:185], v[202:205], v[138:141]
	v_mfma_f32_16x16x32_bf16 v[134:137], v[186:189], v[202:205], v[134:137]
	v_mfma_f32_16x16x32_bf16 v[130:133], v[190:193], v[202:205], v[130:133]
	ds_read_b128 v[202:205], v236 offset:6144
	ds_read_b128 v[246:249], v232 offset:18432
	s_waitcnt lgkmcnt(6)
	v_mfma_f32_16x16x32_bf16 v[126:129], v[178:181], v[206:209], v[126:129]
	v_mfma_f32_16x16x32_bf16 v[122:125], v[182:185], v[206:209], v[122:125]
	v_mfma_f32_16x16x32_bf16 v[118:121], v[186:189], v[206:209], v[118:121]
	v_mfma_f32_16x16x32_bf16 v[114:117], v[190:193], v[206:209], v[114:117]
	ds_read_b128 v[206:209], v236 offset:7168
	ds_read_b128 v[222:225], v232 offset:19456
	s_sub_i32 s38, s35, s6
	v_add_u32_e32 v235, s38, v235
	v_add_u32_e32 v236, s38, v236
	s_waitcnt lgkmcnt(7)
	v_mfma_f32_16x16x32_bf16 v[110:113], v[178:181], v[194:197], v[110:113]
	v_mfma_f32_16x16x32_bf16 v[106:109], v[182:185], v[194:197], v[106:109]
	v_mfma_f32_16x16x32_bf16 v[102:105], v[186:189], v[194:197], v[102:105]
	v_mfma_f32_16x16x32_bf16 v[98:101], v[190:193], v[194:197], v[98:101]
	ds_read_b128 v[194:197], v237
	s_waitcnt lgkmcnt(6)
	v_mfma_f32_16x16x32_bf16 v[94:97], v[178:181], v[198:201], v[94:97]
	v_mfma_f32_16x16x32_bf16 v[90:93], v[182:185], v[198:201], v[90:93]
	v_mfma_f32_16x16x32_bf16 v[86:89], v[186:189], v[198:201], v[86:89]
	v_mfma_f32_16x16x32_bf16 v[82:85], v[190:193], v[198:201], v[82:85]
	ds_read_b128 v[198:201], v237 offset:1024
	s_waitcnt lgkmcnt(5)
	v_mfma_f32_16x16x32_bf16 v[78:81], v[178:181], v[202:205], v[78:81]
	v_mfma_f32_16x16x32_bf16 v[74:77], v[182:185], v[202:205], v[74:77]
	v_mfma_f32_16x16x32_bf16 v[70:73], v[186:189], v[202:205], v[70:73]
	v_mfma_f32_16x16x32_bf16 v[66:69], v[190:193], v[202:205], v[66:69]
	ds_read_b128 v[202:205], v237 offset:2048
	s_waitcnt lgkmcnt(4)
	v_mfma_f32_16x16x32_bf16 v[62:65], v[178:181], v[206:209], v[62:65]
	v_mfma_f32_16x16x32_bf16 v[58:61], v[182:185], v[206:209], v[58:61]
	v_mfma_f32_16x16x32_bf16 v[54:57], v[186:189], v[206:209], v[54:57]
	v_mfma_f32_16x16x32_bf16 v[50:53], v[190:193], v[206:209], v[50:53]
	ds_read_b128 v[206:209], v237 offset:3072
	s_barrier
	s_setprio 1
	s_waitcnt lgkmcnt(3)
	v_mfma_f32_16x16x32_bf16 v[174:177], v[238:241], v[194:197], v[174:177]
	v_mfma_f32_16x16x32_bf16 v[170:173], v[242:245], v[194:197], v[170:173]
	v_mfma_f32_16x16x32_bf16 v[166:169], v[246:249], v[194:197], v[166:169]
	v_mfma_f32_16x16x32_bf16 v[162:165], v[222:225], v[194:197], v[162:165]
	ds_read_b128 v[194:197], v237 offset:4096
	s_waitcnt lgkmcnt(3)
	v_mfma_f32_16x16x32_bf16 v[158:161], v[238:241], v[198:201], v[158:161]
	v_mfma_f32_16x16x32_bf16 v[154:157], v[242:245], v[198:201], v[154:157]
	v_mfma_f32_16x16x32_bf16 v[150:153], v[246:249], v[198:201], v[150:153]
	v_mfma_f32_16x16x32_bf16 v[146:149], v[222:225], v[198:201], v[146:149]
	ds_read_b128 v[198:201], v237 offset:5120
	s_waitcnt lgkmcnt(3)
	v_mfma_f32_16x16x32_bf16 v[142:145], v[238:241], v[202:205], v[142:145]
	v_mfma_f32_16x16x32_bf16 v[138:141], v[242:245], v[202:205], v[138:141]
	v_mfma_f32_16x16x32_bf16 v[134:137], v[246:249], v[202:205], v[134:137]
	v_mfma_f32_16x16x32_bf16 v[130:133], v[222:225], v[202:205], v[130:133]
	ds_read_b128 v[202:205], v237 offset:6144
	s_waitcnt lgkmcnt(3)
	v_mfma_f32_16x16x32_bf16 v[126:129], v[238:241], v[206:209], v[126:129]
	v_mfma_f32_16x16x32_bf16 v[122:125], v[242:245], v[206:209], v[122:125]
	v_mfma_f32_16x16x32_bf16 v[118:121], v[246:249], v[206:209], v[118:121]
	v_mfma_f32_16x16x32_bf16 v[114:117], v[222:225], v[206:209], v[114:117]
	ds_read_b128 v[206:209], v237 offset:7168
	s_sub_i32 s38, s6, s7
	v_add_u32_e32 v232, s38, v232
	v_add_u32_e32 v237, s38, v237
	s_waitcnt lgkmcnt(3)
	v_mfma_f32_16x16x32_bf16 v[110:113], v[238:241], v[194:197], v[110:113]
	v_mfma_f32_16x16x32_bf16 v[106:109], v[242:245], v[194:197], v[106:109]
	v_mfma_f32_16x16x32_bf16 v[102:105], v[246:249], v[194:197], v[102:105]
	v_mfma_f32_16x16x32_bf16 v[98:101], v[222:225], v[194:197], v[98:101]
	s_waitcnt lgkmcnt(2)
	v_mfma_f32_16x16x32_bf16 v[94:97], v[238:241], v[198:201], v[94:97]
	v_mfma_f32_16x16x32_bf16 v[90:93], v[242:245], v[198:201], v[90:93]
	v_mfma_f32_16x16x32_bf16 v[86:89], v[246:249], v[198:201], v[86:89]
	v_mfma_f32_16x16x32_bf16 v[82:85], v[222:225], v[198:201], v[82:85]
	s_waitcnt lgkmcnt(1)
	v_mfma_f32_16x16x32_bf16 v[78:81], v[238:241], v[202:205], v[78:81]
	v_mfma_f32_16x16x32_bf16 v[74:77], v[242:245], v[202:205], v[74:77]
	v_mfma_f32_16x16x32_bf16 v[70:73], v[246:249], v[202:205], v[70:73]
	v_mfma_f32_16x16x32_bf16 v[66:69], v[222:225], v[202:205], v[66:69]
	s_waitcnt lgkmcnt(0)
	v_mfma_f32_16x16x32_bf16 v[62:65], v[238:241], v[206:209], v[62:65]
	v_mfma_f32_16x16x32_bf16 v[58:61], v[242:245], v[206:209], v[58:61]
	v_mfma_f32_16x16x32_bf16 v[54:57], v[246:249], v[206:209], v[54:57]
	v_mfma_f32_16x16x32_bf16 v[50:53], v[222:225], v[206:209], v[50:53]
	s_setprio 0
	s_barrier
	s_mov_b32 s38, s35
	s_mov_b32 s35, s7
	s_mov_b32 s7, s6
	s_mov_b32 s6, s38
	s_nop 7

; template <int MODE>
; __device__ void gemm_tile2(const u16* __restrict__ X, int lda, const u16* __restrict__ W, int ldb, int K,
;                            int m0, int n0, u16* __restrict__ outb, int vbase,
;                            const float* resid, float* outf, unsigned char* smem) {
;     ...
;   G2_GLOAD(0, 0);
;   G2_GLOAD(1, 1);
;   __syncthreads();
;   G2_LSTORE(0, 0);
;   G2_GLOAD(0, 2);
;   __syncthreads();
;   for (int kt2 = 0; kt2 < nk; kt2 += 2) {
; #pragma unroll
;     for (int h = 0; h < 2; ++h) {
;       const int kt = kt2 + h;
;       const u16* st = sbase + h * G2STAGE;
;       bf16x8 fw[4], fx[4];
; #pragma unroll
;       for (int j = 0; j < 4; ++j) fw[j] = *(const bf16x8*)(st + 256 * G2S + (ww * 64 + j * 16 + l15) * G2S + fsw);
; #pragma unroll
;       for (int i = 0; i < 4; ++i) fx[i] = *(const bf16x8*)(st + (wx * 128 + i * 16 + l15) * G2S + fsw);
;       __builtin_amdgcn_sched_barrier(0);
;       __builtin_amdgcn_s_setprio(1);
; #pragma unroll
;       for (int i = 0; i < 4; ++i) {
; #pragma unroll
;         for (int j = 0; j < 4; ++j) {
;           if (MODE == 1) acc[i][j] = mfma16(fx[i], fw[j], acc[i][j]);
;           else acc[i][j] = mfma16(fw[j], fx[i], acc[i][j]);
;         }
;       }
;       __builtin_amdgcn_s_setprio(0);
;       __builtin_amdgcn_sched_barrier(0);
; #pragma unroll
;       for (int i = 0; i < 4; ++i) fx[i] = *(const bf16x8*)(st + (wx * 128 + (i + 4) * 16 + l15) * G2S + fsw);
;       __builtin_amdgcn_sched_barrier(0);
;       if (kt + 1 < nk) G2_LSTORE(1 - h, 1 - h);
;       if (kt + 3 < nk) G2_GLOAD(1 - h, kt + 3);
;       __builtin_amdgcn_sched_barrier(0);
;       __builtin_amdgcn_s_setprio(1);
; #pragma unroll
;       for (int i = 0; i < 4; ++i) {
; #pragma unroll
;         for (int j = 0; j < 4; ++j) {
;           if (MODE == 1) acc[i + 4][j] = mfma16(fx[i], fw[j], acc[i + 4][j]);
;           else acc[i + 4][j] = mfma16(fw[j], fx[i], acc[i + 4][j]);
;         }
;       }
;       __builtin_amdgcn_s_setprio(0);
;       __syncthreads();
;     }
.Lf1_loop:
	s_waitcnt lgkmcnt(3)
	v_mfma_f32_16x16x32_bf16 v[174:177], v[194:197], v[178:181], v[174:177]
	v_mfma_f32_16x16x32_bf16 v[170:173], v[194:197], v[182:185], v[170:173]
	v_mfma_f32_16x16x32_bf16 v[166:169], v[194:197], v[186:189], v[166:169]
	v_mfma_f32_16x16x32_bf16 v[162:165], v[194:197], v[190:193], v[162:165]
	ds_read_b128 v[194:197], v237 offset:4096
	ds_read_b128 v[238:241], v233 offset:16384
	s_waitcnt lgkmcnt(4)
	v_mfma_f32_16x16x32_bf16 v[158:161], v[198:201], v[178:181], v[158:161]
	v_mfma_f32_16x16x32_bf16 v[154:157], v[198:201], v[182:185], v[154:157]
	v_mfma_f32_16x16x32_bf16 v[150:153], v[198:201], v[186:189], v[150:153]
	v_mfma_f32_16x16x32_bf16 v[146:149], v[198:201], v[190:193], v[146:149]
	ds_read_b128 v[198:201], v237 offset:5120
	ds_read_b128 v[242:245], v233 offset:17408
	s_waitcnt lgkmcnt(5)
	v_mfma_f32_16x16x32_bf16 v[142:145], v[202:205], v[178:181], v[142:145]
	v_mfma_f32_16x16x32_bf16 v[138:141], v[202:205], v[182:185], v[138:141]
	v_mfma_f32_16x16x32_bf16 v[134:137], v[202:205], v[186:189], v[134:137]
	v_mfma_f32_16x16x32_bf16 v[130:133], v[202:205], v[190:193], v[130:133]
	ds_read_b128 v[202:205], v237 offset:6144
	ds_read_b128 v[246:249], v233 offset:18432
	s_waitcnt lgkmcnt(6)
	v_mfma_f32_16x16x32_bf16 v[126:129], v[206:209], v[178:181], v[126:129]
	v_mfma_f32_16x16x32_bf16 v[122:125], v[206:209], v[182:185], v[122:125]
	v_mfma_f32_16x16x32_bf16 v[118:121], v[206:209], v[186:189], v[118:121]
	v_mfma_f32_16x16x32_bf16 v[114:117], v[206:209], v[190:193], v[114:117]
	ds_read_b128 v[206:209], v237 offset:7168
	ds_read_b128 v[222:225], v233 offset:19456
	s_sub_i32 s35, s7, s1
	v_add_u32_e32 v236, s35, v236
	v_add_u32_e32 v237, s35, v237
	s_waitcnt lgkmcnt(7)
	v_mfma_f32_16x16x32_bf16 v[110:113], v[194:197], v[178:181], v[110:113]
	v_mfma_f32_16x16x32_bf16 v[106:109], v[194:197], v[182:185], v[106:109]
	v_mfma_f32_16x16x32_bf16 v[102:105], v[194:197], v[186:189], v[102:105]
	v_mfma_f32_16x16x32_bf16 v[98:101], v[194:197], v[190:193], v[98:101]
	ds_read_b128 v[194:197], v232
	s_waitcnt lgkmcnt(6)
	v_mfma_f32_16x16x32_bf16 v[94:97], v[198:201], v[178:181], v[94:97]
	v_mfma_f32_16x16x32_bf16 v[90:93], v[198:201], v[182:185], v[90:93]
	v_mfma_f32_16x16x32_bf16 v[86:89], v[198:201], v[186:189], v[86:89]
	v_mfma_f32_16x16x32_bf16 v[82:85], v[198:201], v[190:193], v[82:85]
	ds_read_b128 v[198:201], v232 offset:1024
	s_waitcnt lgkmcnt(5)
	v_mfma_f32_16x16x32_bf16 v[78:81], v[202:205], v[178:181], v[78:81]
	v_mfma_f32_16x16x32_bf16 v[74:77], v[202:205], v[182:185], v[74:77]
	v_mfma_f32_16x16x32_bf16 v[70:73], v[202:205], v[186:189], v[70:73]
	v_mfma_f32_16x16x32_bf16 v[66:69], v[202:205], v[190:193], v[66:69]
	ds_read_b128 v[202:205], v232 offset:2048
	s_waitcnt lgkmcnt(4)
	v_mfma_f32_16x16x32_bf16 v[62:65], v[206:209], v[178:181], v[62:65]
	v_mfma_f32_16x16x32_bf16 v[58:61], v[206:209], v[182:185], v[58:61]
	v_mfma_f32_16x16x32_bf16 v[54:57], v[206:209], v[186:189], v[54:57]
	v_mfma_f32_16x16x32_bf16 v[50:53], v[206:209], v[190:193], v[50:53]
	ds_read_b128 v[206:209], v232 offset:3072
	s_sub_i32 s35, s1, s7
	v_mad_i32_i24 v235, v221, s35, v220
	v_add_u32_e32 v235, s7, v235
	s_barrier
	s_setprio 1
	s_waitcnt lgkmcnt(3)
	v_mfma_f32_16x16x32_bf16 v[174:177], v[194:197], v[238:241], v[174:177]
	v_mfma_f32_16x16x32_bf16 v[170:173], v[194:197], v[242:245], v[170:173]
	v_mfma_f32_16x16x32_bf16 v[166:169], v[194:197], v[246:249], v[166:169]
	v_mfma_f32_16x16x32_bf16 v[162:165], v[194:197], v[222:225], v[162:165]
	ds_read_b128 v[194:197], v232 offset:4096
	s_waitcnt vmcnt(11)
	ds_write_b128 v235, v[2:5]
	s_waitcnt vmcnt(10)
	ds_write_b128 v235, v[6:9] offset:2048
	buffer_load_dwordx4 v[2:5], v218, s[24:27], 0 offen
	buffer_load_dwordx4 v[6:9], v219, s[24:27], 0 offen
	s_waitcnt lgkmcnt(5)
	v_mfma_f32_16x16x32_bf16 v[158:161], v[198:201], v[238:241], v[158:161]
	v_mfma_f32_16x16x32_bf16 v[154:157], v[198:201], v[242:245], v[154:157]
	v_mfma_f32_16x16x32_bf16 v[150:153], v[198:201], v[246:249], v[150:153]
	v_mfma_f32_16x16x32_bf16 v[146:149], v[198:201], v[222:225], v[146:149]
	ds_read_b128 v[198:201], v232 offset:5120
	s_waitcnt vmcnt(11)
	ds_write_b128 v235, v[10:13] offset:4096
	buffer_load_dwordx4 v[10:13], v218, s[24:27], s27 offen
	s_waitcnt lgkmcnt(6)
	v_mfma_f32_16x16x32_bf16 v[142:145], v[202:205], v[238:241], v[142:145]
	v_mfma_f32_16x16x32_bf16 v[138:141], v[202:205], v[242:245], v[138:141]
	v_mfma_f32_16x16x32_bf16 v[134:137], v[202:205], v[246:249], v[134:137]
	v_mfma_f32_16x16x32_bf16 v[130:133], v[202:205], v[222:225], v[130:133]
	ds_read_b128 v[202:205], v232 offset:6144
	s_waitcnt vmcnt(11)
	ds_write_b128 v235, v[14:17] offset:6144
	s_waitcnt vmcnt(10)
	ds_write_b128 v235, v[18:21] offset:8192
	buffer_load_dwordx4 v[14:17], v219, s[24:27], s27 offen
	buffer_load_dwordx4 v[18:21], v218, s[24:27], s77 offen
	s_waitcnt lgkmcnt(8)
	v_mfma_f32_16x16x32_bf16 v[126:129], v[206:209], v[238:241], v[126:129]
	v_mfma_f32_16x16x32_bf16 v[122:125], v[206:209], v[242:245], v[122:125]
	v_mfma_f32_16x16x32_bf16 v[118:121], v[206:209], v[246:249], v[118:121]
	v_mfma_f32_16x16x32_bf16 v[114:117], v[206:209], v[222:225], v[114:117]
	ds_read_b128 v[206:209], v232 offset:7168
	s_sub_i32 s35, s1, s6
	v_add_u32_e32 v233, s35, v233
	v_add_u32_e32 v232, s35, v232
	s_waitcnt vmcnt(11)
	ds_write_b128 v235, v[22:25] offset:10240
	buffer_load_dwordx4 v[22:25], v219, s[24:27], s77 offen
	s_waitcnt lgkmcnt(9)
	v_mfma_f32_16x16x32_bf16 v[110:113], v[194:197], v[238:241], v[110:113]
	v_mfma_f32_16x16x32_bf16 v[106:109], v[194:197], v[242:245], v[106:109]
	v_mfma_f32_16x16x32_bf16 v[102:105], v[194:197], v[246:249], v[102:105]
	v_mfma_f32_16x16x32_bf16 v[98:101], v[194:197], v[222:225], v[98:101]
	s_waitcnt vmcnt(11)
; template <int MODE>
; __device__ void gemm_tile2(const u16* __restrict__ X, int lda, const u16* __restrict__ W, int ldb, int K,
;                            int m0, int n0, u16* __restrict__ outb, int vbase,
;                            const float* resid, float* outf, unsigned char* smem) {
;     ...
;   G2_GLOAD(0, 0);
;   G2_GLOAD(1, 1);
;   __syncthreads();
;   G2_LSTORE(0, 0);
;   G2_GLOAD(0, 2);
;   __syncthreads();
;   for (int kt2 = 0; kt2 < nk; kt2 += 2) {
; #pragma unroll
;     for (int h = 0; h < 2; ++h) {
;       const int kt = kt2 + h;
;       const u16* st = sbase + h * G2STAGE;
;       bf16x8 fw[4], fx[4];
; #pragma unroll
;       for (int j = 0; j < 4; ++j) fw[j] = *(const bf16x8*)(st + 256 * G2S + (ww * 64 + j * 16 + l15) * G2S + fsw);
; #pragma unroll
;       for (int i = 0; i < 4; ++i) fx[i] = *(const bf16x8*)(st + (wx * 128 + i * 16 + l15) * G2S + fsw);
;       __builtin_amdgcn_sched_barrier(0);
;       __builtin_amdgcn_s_setprio(1);
; #pragma unroll
;       for (int i = 0; i < 4; ++i) {
; #pragma unroll
;         for (int j = 0; j < 4; ++j) {
;           if (MODE == 1) acc[i][j] = mfma16(fx[i], fw[j], acc[i][j]);
;           else acc[i][j] = mfma16(fw[j], fx[i], acc[i][j]);
;         }
;       }
;       __builtin_amdgcn_s_setprio(0);
;       __builtin_amdgcn_sched_barrier(0);
; #pragma unroll
;       for (int i = 0; i < 4; ++i) fx[i] = *(const bf16x8*)(st + (wx * 128 + (i + 4) * 16 + l15) * G2S + fsw);
;       __builtin_amdgcn_sched_barrier(0);
;       if (kt + 1 < nk) G2_LSTORE(1 - h, 1 - h);
;       if (kt + 3 < nk) G2_GLOAD(1 - h, kt + 3);
;       __builtin_amdgcn_sched_barrier(0);
;       __builtin_amdgcn_s_setprio(1);
; #pragma unroll
;       for (int i = 0; i < 4; ++i) {
; #pragma unroll
;         for (int j = 0; j < 4; ++j) {
;           if (MODE == 1) acc[i + 4][j] = mfma16(fx[i], fw[j], acc[i + 4][j]);
;           else acc[i + 4][j] = mfma16(fw[j], fx[i], acc[i + 4][j]);
;         }
;       }
;       __builtin_amdgcn_s_setprio(0);
;       __syncthreads();
;     }
	ds_write_b128 v235, v[26:29] offset:12288
	s_waitcnt vmcnt(10)
	ds_write_b128 v235, v[30:33] offset:14336
	buffer_load_dwordx4 v[26:29], v218, s[24:27], s78 offen
	buffer_load_dwordx4 v[30:33], v219, s[24:27], s78 offen
	s_waitcnt lgkmcnt(8)
	v_mfma_f32_16x16x32_bf16 v[94:97], v[198:201], v[238:241], v[94:97]
	v_mfma_f32_16x16x32_bf16 v[90:93], v[198:201], v[242:245], v[90:93]
	v_mfma_f32_16x16x32_bf16 v[86:89], v[198:201], v[246:249], v[86:89]
	v_mfma_f32_16x16x32_bf16 v[82:85], v[198:201], v[222:225], v[82:85]
	s_waitcnt vmcnt(11)
	ds_write_b128 v235, v[34:37] offset:16384
	buffer_load_dwordx4 v[34:37], v218, s[40:43], 0 offen
	s_waitcnt lgkmcnt(7)
	v_mfma_f32_16x16x32_bf16 v[78:81], v[202:205], v[238:241], v[78:81]
	v_mfma_f32_16x16x32_bf16 v[74:77], v[202:205], v[242:245], v[74:77]
	v_mfma_f32_16x16x32_bf16 v[70:73], v[202:205], v[246:249], v[70:73]
	v_mfma_f32_16x16x32_bf16 v[66:69], v[202:205], v[222:225], v[66:69]
	s_waitcnt vmcnt(11)
	ds_write_b128 v235, v[38:41] offset:18432
	s_waitcnt vmcnt(10)
	ds_write_b128 v235, v[42:45] offset:20480
	buffer_load_dwordx4 v[38:41], v219, s[40:43], 0 offen
	buffer_load_dwordx4 v[42:45], v218, s[40:43], s27 offen
	s_waitcnt lgkmcnt(6)
	v_mfma_f32_16x16x32_bf16 v[62:65], v[206:209], v[238:241], v[62:65]
	v_mfma_f32_16x16x32_bf16 v[58:61], v[206:209], v[242:245], v[58:61]
	v_mfma_f32_16x16x32_bf16 v[54:57], v[206:209], v[246:249], v[54:57]
	v_mfma_f32_16x16x32_bf16 v[50:53], v[206:209], v[222:225], v[50:53]
	s_waitcnt vmcnt(11)
	ds_write_b128 v235, v[46:49] offset:22528
	buffer_load_dwordx4 v[46:49], v219, s[40:43], s27 offen
	v_add_u32_e32 v218, 0x80, v218
	v_add_u32_e32 v219, 0x80, v219
	s_waitcnt lgkmcnt(0)
	s_setprio 0
	s_barrier
	s_mov_b32 s35, s7
	s_mov_b32 s7, s6
	s_mov_b32 s6, s1
	s_mov_b32 s1, s35
	ds_read_b128 v[178:181], v236 offset:16384
	ds_read_b128 v[182:185], v236 offset:17408
	ds_read_b128 v[186:189], v236 offset:18432
	ds_read_b128 v[190:193], v236 offset:19456
	ds_read_b128 v[194:197], v237
	ds_read_b128 v[198:201], v237 offset:1024
	ds_read_b128 v[202:205], v237 offset:2048
	ds_read_b128 v[206:209], v237 offset:3072
	s_add_u32 s0, s0, 1
	s_cmp_lt_u32 s0, 14
	s_cbranch_scc1 .Lf1_loop
	s_waitcnt lgkmcnt(3)
	v_mfma_f32_16x16x32_bf16 v[174:177], v[194:197], v[178:181], v[174:177]
	v_mfma_f32_16x16x32_bf16 v[170:173], v[194:197], v[182:185], v[170:173]
	v_mfma_f32_16x16x32_bf16 v[166:169], v[194:197], v[186:189], v[166:169]
	v_mfma_f32_16x16x32_bf16 v[162:165], v[194:197], v[190:193], v[162:165]
	ds_read_b128 v[194:197], v237 offset:4096
	ds_read_b128 v[238:241], v233 offset:16384
	s_waitcnt lgkmcnt(4)
	v_mfma_f32_16x16x32_bf16 v[158:161], v[198:201], v[178:181], v[158:161]
	v_mfma_f32_16x16x32_bf16 v[154:157], v[198:201], v[182:185], v[154:157]
	v_mfma_f32_16x16x32_bf16 v[150:153], v[198:201], v[186:189], v[150:153]
	v_mfma_f32_16x16x32_bf16 v[146:149], v[198:201], v[190:193], v[146:149]
	ds_read_b128 v[198:201], v237 offset:5120
	ds_read_b128 v[242:245], v233 offset:17408
	s_waitcnt lgkmcnt(5)
	v_mfma_f32_16x16x32_bf16 v[142:145], v[202:205], v[178:181], v[142:145]
	v_mfma_f32_16x16x32_bf16 v[138:141], v[202:205], v[182:185], v[138:141]
	v_mfma_f32_16x16x32_bf16 v[134:137], v[202:205], v[186:189], v[134:137]
	v_mfma_f32_16x16x32_bf16 v[130:133], v[202:205], v[190:193], v[130:133]
	ds_read_b128 v[202:205], v237 offset:6144
	ds_read_b128 v[246:249], v233 offset:18432
	s_waitcnt lgkmcnt(6)
	v_mfma_f32_16x16x32_bf16 v[126:129], v[206:209], v[178:181], v[126:129]
	v_mfma_f32_16x16x32_bf16 v[122:125], v[206:209], v[182:185], v[122:125]
	v_mfma_f32_16x16x32_bf16 v[118:121], v[206:209], v[186:189], v[118:121]
	v_mfma_f32_16x16x32_bf16 v[114:117], v[206:209], v[190:193], v[114:117]
	ds_read_b128 v[206:209], v237 offset:7168
	ds_read_b128 v[222:225], v233 offset:19456
	s_sub_i32 s35, s7, s1
	v_add_u32_e32 v236, s35, v236
	v_add_u32_e32 v237, s35, v237
	s_waitcnt lgkmcnt(7)
	v_mfma_f32_16x16x32_bf16 v[110:113], v[194:197], v[178:181], v[110:113]
	v_mfma_f32_16x16x32_bf16 v[106:109], v[194:197], v[182:185], v[106:109]
	v_mfma_f32_16x16x32_bf16 v[102:105], v[194:197], v[186:189], v[102:105]
	v_mfma_f32_16x16x32_bf16 v[98:101], v[194:197], v[190:193], v[98:101]
	ds_read_b128 v[194:197], v232
	s_waitcnt lgkmcnt(6)
	v_mfma_f32_16x16x32_bf16 v[94:97], v[198:201], v[178:181], v[94:97]
	v_mfma_f32_16x16x32_bf16 v[90:93], v[198:201], v[182:185], v[90:93]
	v_mfma_f32_16x16x32_bf16 v[86:89], v[198:201], v[186:189], v[86:89]
	v_mfma_f32_16x16x32_bf16 v[82:85], v[198:201], v[190:193], v[82:85]
	ds_read_b128 v[198:201], v232 offset:1024
	s_waitcnt lgkmcnt(5)
	v_mfma_f32_16x16x32_bf16 v[78:81], v[202:205], v[178:181], v[78:81]
	v_mfma_f32_16x16x32_bf16 v[74:77], v[202:205], v[182:185], v[74:77]
	v_mfma_f32_16x16x32_bf16 v[70:73], v[202:205], v[186:189], v[70:73]
	v_mfma_f32_16x16x32_bf16 v[66:69], v[202:205], v[190:193], v[66:69]
	ds_read_b128 v[202:205], v232 offset:2048
	s_waitcnt lgkmcnt(4)
	v_mfma_f32_16x16x32_bf16 v[62:65], v[206:209], v[178:181], v[62:65]
	v_mfma_f32_16x16x32_bf16 v[58:61], v[206:209], v[182:185], v[58:61]
	v_mfma_f32_16x16x32_bf16 v[54:57], v[206:209], v[186:189], v[54:57]
	v_mfma_f32_16x16x32_bf16 v[50:53], v[206:209], v[190:193], v[50:53]
	ds_read_b128 v[206:209], v232 offset:3072
	s_sub_i32 s35, s1, s7
	v_mad_i32_i24 v235, v221, s35, v220
	v_add_u32_e32 v235, s7, v235
	s_barrier
; template <int MODE>
; __device__ void gemm_tile2(const u16* __restrict__ X, int lda, const u16* __restrict__ W, int ldb, int K,
;                            int m0, int n0, u16* __restrict__ outb, int vbase,
;                            const float* resid, float* outf, unsigned char* smem) {
;     ...
; #pragma unroll
;       for (int i = 0; i < 4; ++i) fx[i] = *(const bf16x8*)(st + (wx * 128 + (i + 4) * 16 + l15) * G2S + fsw);
;       __builtin_amdgcn_sched_barrier(0);
;       if (kt + 1 < nk) G2_LSTORE(1 - h, 1 - h);
;       if (kt + 3 < nk) G2_GLOAD(1 - h, kt + 3);
;       __builtin_amdgcn_sched_barrier(0);
;       __builtin_amdgcn_s_setprio(1);
; #pragma unroll
;       for (int i = 0; i < 4; ++i) {
; #pragma unroll
;         for (int j = 0; j < 4; ++j) {
;           if (MODE == 1) acc[i + 4][j] = mfma16(fx[i], fw[j], acc[i + 4][j]);
;           else acc[i + 4][j] = mfma16(fw[j], fx[i], acc[i + 4][j]);
;         }
;       }
;       __builtin_amdgcn_s_setprio(0);
;       __syncthreads();
	s_setprio 1
	s_waitcnt lgkmcnt(3)
	v_mfma_f32_16x16x32_bf16 v[174:177], v[194:197], v[238:241], v[174:177]
	v_mfma_f32_16x16x32_bf16 v[170:173], v[194:197], v[242:245], v[170:173]
	v_mfma_f32_16x16x32_bf16 v[166:169], v[194:197], v[246:249], v[166:169]
	v_mfma_f32_16x16x32_bf16 v[162:165], v[194:197], v[222:225], v[162:165]
	ds_read_b128 v[194:197], v232 offset:4096
	s_waitcnt vmcnt(11)
	ds_write_b128 v235, v[2:5]
	s_waitcnt vmcnt(10)
	ds_write_b128 v235, v[6:9] offset:2048
	s_waitcnt lgkmcnt(5)
	v_mfma_f32_16x16x32_bf16 v[158:161], v[198:201], v[238:241], v[158:161]
	v_mfma_f32_16x16x32_bf16 v[154:157], v[198:201], v[242:245], v[154:157]
	v_mfma_f32_16x16x32_bf16 v[150:153], v[198:201], v[246:249], v[150:153]
	v_mfma_f32_16x16x32_bf16 v[146:149], v[198:201], v[222:225], v[146:149]
	ds_read_b128 v[198:201], v232 offset:5120
	s_waitcnt vmcnt(9)
	ds_write_b128 v235, v[10:13] offset:4096
	s_waitcnt lgkmcnt(6)
	v_mfma_f32_16x16x32_bf16 v[142:145], v[202:205], v[238:241], v[142:145]
	v_mfma_f32_16x16x32_bf16 v[138:141], v[202:205], v[242:245], v[138:141]
	v_mfma_f32_16x16x32_bf16 v[134:137], v[202:205], v[246:249], v[134:137]
	v_mfma_f32_16x16x32_bf16 v[130:133], v[202:205], v[222:225], v[130:133]
	ds_read_b128 v[202:205], v232 offset:6144
	s_waitcnt vmcnt(8)
	ds_write_b128 v235, v[14:17] offset:6144
	s_waitcnt vmcnt(7)
	ds_write_b128 v235, v[18:21] offset:8192
	s_waitcnt lgkmcnt(8)
	v_mfma_f32_16x16x32_bf16 v[126:129], v[206:209], v[238:241], v[126:129]
	v_mfma_f32_16x16x32_bf16 v[122:125], v[206:209], v[242:245], v[122:125]
	v_mfma_f32_16x16x32_bf16 v[118:121], v[206:209], v[246:249], v[118:121]
	v_mfma_f32_16x16x32_bf16 v[114:117], v[206:209], v[222:225], v[114:117]
	ds_read_b128 v[206:209], v232 offset:7168
	s_sub_i32 s35, s1, s6
	v_add_u32_e32 v233, s35, v233
	v_add_u32_e32 v232, s35, v232
	s_waitcnt vmcnt(6)
	ds_write_b128 v235, v[22:25] offset:10240
	s_waitcnt lgkmcnt(9)
	v_mfma_f32_16x16x32_bf16 v[110:113], v[194:197], v[238:241], v[110:113]
	v_mfma_f32_16x16x32_bf16 v[106:109], v[194:197], v[242:245], v[106:109]
	v_mfma_f32_16x16x32_bf16 v[102:105], v[194:197], v[246:249], v[102:105]
	v_mfma_f32_16x16x32_bf16 v[98:101], v[194:197], v[222:225], v[98:101]
	s_waitcnt vmcnt(5)
	ds_write_b128 v235, v[26:29] offset:12288
	s_waitcnt vmcnt(4)
	ds_write_b128 v235, v[30:33] offset:14336
	s_waitcnt lgkmcnt(8)
	v_mfma_f32_16x16x32_bf16 v[94:97], v[198:201], v[238:241], v[94:97]
	v_mfma_f32_16x16x32_bf16 v[90:93], v[198:201], v[242:245], v[90:93]
	v_mfma_f32_16x16x32_bf16 v[86:89], v[198:201], v[246:249], v[86:89]
	v_mfma_f32_16x16x32_bf16 v[82:85], v[198:201], v[222:225], v[82:85]
	s_waitcnt vmcnt(3)
	ds_write_b128 v235, v[34:37] offset:16384
	s_waitcnt lgkmcnt(7)
	v_mfma_f32_16x16x32_bf16 v[78:81], v[202:205], v[238:241], v[78:81]
	v_mfma_f32_16x16x32_bf16 v[74:77], v[202:205], v[242:245], v[74:77]
	v_mfma_f32_16x16x32_bf16 v[70:73], v[202:205], v[246:249], v[70:73]
	v_mfma_f32_16x16x32_bf16 v[66:69], v[202:205], v[222:225], v[66:69]
	s_waitcnt vmcnt(2)
	ds_write_b128 v235, v[38:41] offset:18432
	s_waitcnt vmcnt(1)
	ds_write_b128 v235, v[42:45] offset:20480
	s_waitcnt lgkmcnt(6)
	v_mfma_f32_16x16x32_bf16 v[62:65], v[206:209], v[238:241], v[62:65]
	v_mfma_f32_16x16x32_bf16 v[58:61], v[206:209], v[242:245], v[58:61]
	v_mfma_f32_16x16x32_bf16 v[54:57], v[206:209], v[246:249], v[54:57]
	v_mfma_f32_16x16x32_bf16 v[50:53], v[206:209], v[222:225], v[50:53]
	s_waitcnt vmcnt(0)
	ds_write_b128 v235, v[46:49] offset:22528
	s_waitcnt lgkmcnt(0)
	s_setprio 0
	s_barrier
; template <int MODE>
; __device__ void gemm_tile2(const u16* __restrict__ X, int lda, const u16* __restrict__ W, int ldb, int K,
;                            int m0, int n0, u16* __restrict__ outb, int vbase,
;                            const float* resid, float* outf, unsigned char* smem) {
;     ...
;   for (int kt2 = 0; kt2 < nk; kt2 += 2) {
; #pragma unroll
;     for (int h = 0; h < 2; ++h) {
;       const int kt = kt2 + h;
;       const u16* st = sbase + h * G2STAGE;
;       bf16x8 fw[4], fx[4];
; #pragma unroll
;       for (int j = 0; j < 4; ++j) fw[j] = *(const bf16x8*)(st + 256 * G2S + (ww * 64 + j * 16 + l15) * G2S + fsw);
; #pragma unroll
;       for (int i = 0; i < 4; ++i) fx[i] = *(const bf16x8*)(st + (wx * 128 + i * 16 + l15) * G2S + fsw);
;       __builtin_amdgcn_sched_barrier(0);
;       __builtin_amdgcn_s_setprio(1);
; #pragma unroll
;       for (int i = 0; i < 4; ++i) {
; #pragma unroll
;         for (int j = 0; j < 4; ++j) {
;           if (MODE == 1) acc[i][j] = mfma16(fx[i], fw[j], acc[i][j]);
;           else acc[i][j] = mfma16(fw[j], fx[i], acc[i][j]);
;         }
;       }
;       __builtin_amdgcn_s_setprio(0);
;       __builtin_amdgcn_sched_barrier(0);
; #pragma unroll
;       for (int i = 0; i < 4; ++i) fx[i] = *(const bf16x8*)(st + (wx * 128 + (i + 4) * 16 + l15) * G2S + fsw);
;       __builtin_amdgcn_sched_barrier(0);
;       if (kt + 1 < nk) G2_LSTORE(1 - h, 1 - h);
;       if (kt + 3 < nk) G2_GLOAD(1 - h, kt + 3);
;       __builtin_amdgcn_sched_barrier(0);
;       __builtin_amdgcn_s_setprio(1);
; #pragma unroll
;       for (int i = 0; i < 4; ++i) {
; #pragma unroll
;         for (int j = 0; j < 4; ++j) {
;           if (MODE == 1) acc[i + 4][j] = mfma16(fx[i], fw[j], acc[i + 4][j]);
;           else acc[i + 4][j] = mfma16(fw[j], fx[i], acc[i + 4][j]);
;         }
;       }
;       __builtin_amdgcn_s_setprio(0);
;       __syncthreads();
;     }
;   }
	s_mov_b32 s35, s7
	s_mov_b32 s7, s6
	s_mov_b32 s6, s1
	s_mov_b32 s1, s35
	ds_read_b128 v[178:181], v236 offset:16384
	ds_read_b128 v[182:185], v236 offset:17408
	ds_read_b128 v[186:189], v236 offset:18432
	ds_read_b128 v[190:193], v236 offset:19456
	ds_read_b128 v[194:197], v237
	ds_read_b128 v[198:201], v237 offset:1024
	ds_read_b128 v[202:205], v237 offset:2048
	ds_read_b128 v[206:209], v237 offset:3072
	s_waitcnt lgkmcnt(3)
	v_mfma_f32_16x16x32_bf16 v[174:177], v[194:197], v[178:181], v[174:177]
	v_mfma_f32_16x16x32_bf16 v[170:173], v[194:197], v[182:185], v[170:173]
	v_mfma_f32_16x16x32_bf16 v[166:169], v[194:197], v[186:189], v[166:169]
	v_mfma_f32_16x16x32_bf16 v[162:165], v[194:197], v[190:193], v[162:165]
	ds_read_b128 v[194:197], v237 offset:4096
	ds_read_b128 v[238:241], v233 offset:16384
	s_waitcnt lgkmcnt(4)
	v_mfma_f32_16x16x32_bf16 v[158:161], v[198:201], v[178:181], v[158:161]
	v_mfma_f32_16x16x32_bf16 v[154:157], v[198:201], v[182:185], v[154:157]
	v_mfma_f32_16x16x32_bf16 v[150:153], v[198:201], v[186:189], v[150:153]
	v_mfma_f32_16x16x32_bf16 v[146:149], v[198:201], v[190:193], v[146:149]
	ds_read_b128 v[198:201], v237 offset:5120
	ds_read_b128 v[242:245], v233 offset:17408
	s_waitcnt lgkmcnt(5)
	v_mfma_f32_16x16x32_bf16 v[142:145], v[202:205], v[178:181], v[142:145]
	v_mfma_f32_16x16x32_bf16 v[138:141], v[202:205], v[182:185], v[138:141]
	v_mfma_f32_16x16x32_bf16 v[134:137], v[202:205], v[186:189], v[134:137]
	v_mfma_f32_16x16x32_bf16 v[130:133], v[202:205], v[190:193], v[130:133]
	ds_read_b128 v[202:205], v237 offset:6144
	ds_read_b128 v[246:249], v233 offset:18432
	s_waitcnt lgkmcnt(6)
	v_mfma_f32_16x16x32_bf16 v[126:129], v[206:209], v[178:181], v[126:129]
	v_mfma_f32_16x16x32_bf16 v[122:125], v[206:209], v[182:185], v[122:125]
	v_mfma_f32_16x16x32_bf16 v[118:121], v[206:209], v[186:189], v[118:121]
	v_mfma_f32_16x16x32_bf16 v[114:117], v[206:209], v[190:193], v[114:117]
	ds_read_b128 v[206:209], v237 offset:7168
	ds_read_b128 v[222:225], v233 offset:19456
	s_sub_i32 s35, s7, s1
	v_add_u32_e32 v236, s35, v236
	v_add_u32_e32 v237, s35, v237
	s_waitcnt lgkmcnt(7)
	v_mfma_f32_16x16x32_bf16 v[110:113], v[194:197], v[178:181], v[110:113]
	v_mfma_f32_16x16x32_bf16 v[106:109], v[194:197], v[182:185], v[106:109]
	v_mfma_f32_16x16x32_bf16 v[102:105], v[194:197], v[186:189], v[102:105]
	v_mfma_f32_16x16x32_bf16 v[98:101], v[194:197], v[190:193], v[98:101]
	ds_read_b128 v[194:197], v232
	s_waitcnt lgkmcnt(6)
	v_mfma_f32_16x16x32_bf16 v[94:97], v[198:201], v[178:181], v[94:97]
	v_mfma_f32_16x16x32_bf16 v[90:93], v[198:201], v[182:185], v[90:93]
	v_mfma_f32_16x16x32_bf16 v[86:89], v[198:201], v[186:189], v[86:89]
	v_mfma_f32_16x16x32_bf16 v[82:85], v[198:201], v[190:193], v[82:85]
	ds_read_b128 v[198:201], v232 offset:1024
	s_waitcnt lgkmcnt(5)
	v_mfma_f32_16x16x32_bf16 v[78:81], v[202:205], v[178:181], v[78:81]
	v_mfma_f32_16x16x32_bf16 v[74:77], v[202:205], v[182:185], v[74:77]
	v_mfma_f32_16x16x32_bf16 v[70:73], v[202:205], v[186:189], v[70:73]
	v_mfma_f32_16x16x32_bf16 v[66:69], v[202:205], v[190:193], v[66:69]
	ds_read_b128 v[202:205], v232 offset:2048
	s_waitcnt lgkmcnt(4)
	v_mfma_f32_16x16x32_bf16 v[62:65], v[206:209], v[178:181], v[62:65]
	v_mfma_f32_16x16x32_bf16 v[58:61], v[206:209], v[182:185], v[58:61]
	v_mfma_f32_16x16x32_bf16 v[54:57], v[206:209], v[186:189], v[54:57]
	v_mfma_f32_16x16x32_bf16 v[50:53], v[206:209], v[190:193], v[50:53]
	ds_read_b128 v[206:209], v232 offset:3072
	s_barrier
	s_setprio 1
	s_waitcnt lgkmcnt(3)
	v_mfma_f32_16x16x32_bf16 v[174:177], v[194:197], v[238:241], v[174:177]
	v_mfma_f32_16x16x32_bf16 v[170:173], v[194:197], v[242:245], v[170:173]
	v_mfma_f32_16x16x32_bf16 v[166:169], v[194:197], v[246:249], v[166:169]
	v_mfma_f32_16x16x32_bf16 v[162:165], v[194:197], v[222:225], v[162:165]
	ds_read_b128 v[194:197], v232 offset:4096
	s_waitcnt lgkmcnt(3)
	v_mfma_f32_16x16x32_bf16 v[158:161], v[198:201], v[238:241], v[158:161]
	v_mfma_f32_16x16x32_bf16 v[154:157], v[198:201], v[242:245], v[154:157]
	v_mfma_f32_16x16x32_bf16 v[150:153], v[198:201], v[246:249], v[150:153]
	v_mfma_f32_16x16x32_bf16 v[146:149], v[198:201], v[222:225], v[146:149]
	ds_read_b128 v[198:201], v232 offset:5120
	s_waitcnt lgkmcnt(3)
	v_mfma_f32_16x16x32_bf16 v[142:145], v[202:205], v[238:241], v[142:145]
	v_mfma_f32_16x16x32_bf16 v[138:141], v[202:205], v[242:245], v[138:141]
	v_mfma_f32_16x16x32_bf16 v[134:137], v[202:205], v[246:249], v[134:137]
	v_mfma_f32_16x16x32_bf16 v[130:133], v[202:205], v[222:225], v[130:133]
	ds_read_b128 v[202:205], v232 offset:6144
	s_waitcnt lgkmcnt(3)
	v_mfma_f32_16x16x32_bf16 v[126:129], v[206:209], v[238:241], v[126:129]
	v_mfma_f32_16x16x32_bf16 v[122:125], v[206:209], v[242:245], v[122:125]
	v_mfma_f32_16x16x32_bf16 v[118:121], v[206:209], v[246:249], v[118:121]
	v_mfma_f32_16x16x32_bf16 v[114:117], v[206:209], v[222:225], v[114:117]
	ds_read_b128 v[206:209], v232 offset:7168
	s_sub_i32 s35, s1, s6
	v_add_u32_e32 v233, s35, v233
	v_add_u32_e32 v232, s35, v232
	s_waitcnt lgkmcnt(3)
	v_mfma_f32_16x16x32_bf16 v[110:113], v[194:197], v[238:241], v[110:113]
	v_mfma_f32_16x16x32_bf16 v[106:109], v[194:197], v[242:245], v[106:109]
	v_mfma_f32_16x16x32_bf16 v[102:105], v[194:197], v[246:249], v[102:105]
	v_mfma_f32_16x16x32_bf16 v[98:101], v[194:197], v[222:225], v[98:101]
	s_waitcnt lgkmcnt(2)
	v_mfma_f32_16x16x32_bf16 v[94:97], v[198:201], v[238:241], v[94:97]
	v_mfma_f32_16x16x32_bf16 v[90:93], v[198:201], v[242:245], v[90:93]
	v_mfma_f32_16x16x32_bf16 v[86:89], v[198:201], v[246:249], v[86:89]
	v_mfma_f32_16x16x32_bf16 v[82:85], v[198:201], v[222:225], v[82:85]
	s_waitcnt lgkmcnt(1)
	v_mfma_f32_16x16x32_bf16 v[78:81], v[202:205], v[238:241], v[78:81]
	v_mfma_f32_16x16x32_bf16 v[74:77], v[202:205], v[242:245], v[74:77]
	v_mfma_f32_16x16x32_bf16 v[70:73], v[202:205], v[246:249], v[70:73]
	v_mfma_f32_16x16x32_bf16 v[66:69], v[202:205], v[222:225], v[66:69]
	s_waitcnt lgkmcnt(0)
	v_mfma_f32_16x16x32_bf16 v[62:65], v[206:209], v[238:241], v[62:65]
	v_mfma_f32_16x16x32_bf16 v[58:61], v[206:209], v[242:245], v[58:61]
	v_mfma_f32_16x16x32_bf16 v[54:57], v[206:209], v[246:249], v[54:57]
	v_mfma_f32_16x16x32_bf16 v[50:53], v[206:209], v[222:225], v[50:53]
	s_setprio 0
	s_barrier
	s_mov_b32 s35, s7
	s_mov_b32 s7, s6
	s_mov_b32 s6, s1
	s_mov_b32 s1, s35
	s_nop 7
	v_and_b32_e32 v232, 15, v0
	s_branch .LBB0_285

; template <int MODE>
; __device__ void gemm_tile2(const u16* __restrict__ X, int lda, const u16* __restrict__ W, int ldb, int K,
;                            int m0, int n0, u16* __restrict__ outb, int vbase,
;                            const float* resid, float* outf, unsigned char* smem) {
;     ...
;   G2_GLOAD(0, 0);
;   G2_GLOAD(1, 1);
;   __syncthreads();
;   G2_LSTORE(0, 0);
;   G2_GLOAD(0, 2);
;   __syncthreads();
;   for (int kt2 = 0; kt2 < nk; kt2 += 2) {
; #pragma unroll
;     for (int h = 0; h < 2; ++h) {
;       const int kt = kt2 + h;
;       const u16* st = sbase + h * G2STAGE;
;       bf16x8 fw[4], fx[4];
; #pragma unroll
;       for (int j = 0; j < 4; ++j) fw[j] = *(const bf16x8*)(st + 256 * G2S + (ww * 64 + j * 16 + l15) * G2S + fsw);
; #pragma unroll
;       for (int i = 0; i < 4; ++i) fx[i] = *(const bf16x8*)(st + (wx * 128 + i * 16 + l15) * G2S + fsw);
;       __builtin_amdgcn_sched_barrier(0);
;       __builtin_amdgcn_s_setprio(1);
; #pragma unroll
;       for (int i = 0; i < 4; ++i) {
; #pragma unroll
;         for (int j = 0; j < 4; ++j) {
;           if (MODE == 1) acc[i][j] = mfma16(fx[i], fw[j], acc[i][j]);
;           else acc[i][j] = mfma16(fw[j], fx[i], acc[i][j]);
;         }
;       }
;       __builtin_amdgcn_s_setprio(0);
;       __builtin_amdgcn_sched_barrier(0);
; #pragma unroll
;       for (int i = 0; i < 4; ++i) fx[i] = *(const bf16x8*)(st + (wx * 128 + (i + 4) * 16 + l15) * G2S + fsw);
;       __builtin_amdgcn_sched_barrier(0);
;       if (kt + 1 < nk) G2_LSTORE(1 - h, 1 - h);
;       if (kt + 3 < nk) G2_GLOAD(1 - h, kt + 3);
;       __builtin_amdgcn_sched_barrier(0);
;       __builtin_amdgcn_s_setprio(1);
; #pragma unroll
;       for (int i = 0; i < 4; ++i) {
; #pragma unroll
;         for (int j = 0; j < 4; ++j) {
;           if (MODE == 1) acc[i + 4][j] = mfma16(fx[i], fw[j], acc[i + 4][j]);
;           else acc[i + 4][j] = mfma16(fw[j], fx[i], acc[i + 4][j]);
;         }
;       }
;       __builtin_amdgcn_s_setprio(0);
;       __syncthreads();
;     }
.Lf2_loop:
	s_waitcnt lgkmcnt(3)
	v_mfma_f32_16x16x32_bf16 v[126:129], v[178:181], v[194:197], v[126:129]
	v_mfma_f32_16x16x32_bf16 v[122:125], v[182:185], v[194:197], v[122:125]
	v_mfma_f32_16x16x32_bf16 v[118:121], v[186:189], v[194:197], v[118:121]
	v_mfma_f32_16x16x32_bf16 v[114:117], v[190:193], v[194:197], v[114:117]
	ds_read_b128 v[194:197], v236 offset:4096
	ds_read_b128 v[238:241], v232 offset:16384
	s_waitcnt lgkmcnt(4)
	v_mfma_f32_16x16x32_bf16 v[110:113], v[178:181], v[198:201], v[110:113]
	v_mfma_f32_16x16x32_bf16 v[106:109], v[182:185], v[198:201], v[106:109]
	v_mfma_f32_16x16x32_bf16 v[102:105], v[186:189], v[198:201], v[102:105]
	v_mfma_f32_16x16x32_bf16 v[98:101], v[190:193], v[198:201], v[98:101]
	ds_read_b128 v[198:201], v236 offset:5120
	ds_read_b128 v[242:245], v232 offset:17408
	s_waitcnt lgkmcnt(5)
	v_mfma_f32_16x16x32_bf16 v[94:97], v[178:181], v[202:205], v[94:97]
	v_mfma_f32_16x16x32_bf16 v[90:93], v[182:185], v[202:205], v[90:93]
	v_mfma_f32_16x16x32_bf16 v[86:89], v[186:189], v[202:205], v[86:89]
	v_mfma_f32_16x16x32_bf16 v[82:85], v[190:193], v[202:205], v[82:85]
	ds_read_b128 v[202:205], v236 offset:6144
	ds_read_b128 v[246:249], v232 offset:18432
	s_waitcnt lgkmcnt(6)
	v_mfma_f32_16x16x32_bf16 v[78:81], v[178:181], v[206:209], v[78:81]
	v_mfma_f32_16x16x32_bf16 v[74:77], v[182:185], v[206:209], v[74:77]
	v_mfma_f32_16x16x32_bf16 v[70:73], v[186:189], v[206:209], v[70:73]
	v_mfma_f32_16x16x32_bf16 v[66:69], v[190:193], v[206:209], v[66:69]
	ds_read_b128 v[206:209], v236 offset:7168
	ds_read_b128 v[222:225], v232 offset:19456
	s_sub_i32 s35, s31, s7
	v_add_u32_e32 v235, s35, v235
	v_add_u32_e32 v236, s35, v236
	s_waitcnt lgkmcnt(7)
	v_mfma_f32_16x16x32_bf16 v[62:65], v[178:181], v[194:197], v[62:65]
	v_mfma_f32_16x16x32_bf16 v[58:61], v[182:185], v[194:197], v[58:61]
	v_mfma_f32_16x16x32_bf16 v[54:57], v[186:189], v[194:197], v[54:57]
	v_mfma_f32_16x16x32_bf16 v[50:53], v[190:193], v[194:197], v[50:53]
	ds_read_b128 v[194:197], v237
	s_waitcnt lgkmcnt(6)
	v_mfma_f32_16x16x32_bf16 v[46:49], v[178:181], v[198:201], v[46:49]
	v_mfma_f32_16x16x32_bf16 v[42:45], v[182:185], v[198:201], v[42:45]
	v_mfma_f32_16x16x32_bf16 v[38:41], v[186:189], v[198:201], v[38:41]
	v_mfma_f32_16x16x32_bf16 v[34:37], v[190:193], v[198:201], v[34:37]
	ds_read_b128 v[198:201], v237 offset:1024
	s_waitcnt lgkmcnt(5)
	v_mfma_f32_16x16x32_bf16 v[30:33], v[178:181], v[202:205], v[30:33]
	v_mfma_f32_16x16x32_bf16 v[26:29], v[182:185], v[202:205], v[26:29]
	v_mfma_f32_16x16x32_bf16 v[22:25], v[186:189], v[202:205], v[22:25]
	v_mfma_f32_16x16x32_bf16 v[18:21], v[190:193], v[202:205], v[18:21]
	ds_read_b128 v[202:205], v237 offset:2048
	s_waitcnt lgkmcnt(4)
	v_mfma_f32_16x16x32_bf16 v[14:17], v[178:181], v[206:209], v[14:17]
	v_mfma_f32_16x16x32_bf16 v[10:13], v[182:185], v[206:209], v[10:13]
	v_mfma_f32_16x16x32_bf16 v[6:9], v[186:189], v[206:209], v[6:9]
	v_mfma_f32_16x16x32_bf16 v[2:5], v[190:193], v[206:209], v[2:5]
	ds_read_b128 v[206:209], v237 offset:3072
	s_sub_i32 s35, s7, s31
	v_mad_i32_i24 v234, v221, s35, v220
	v_add_u32_e32 v234, s31, v234
	s_barrier
	s_setprio 1
	s_waitcnt lgkmcnt(3)
	v_mfma_f32_16x16x32_bf16 v[126:129], v[238:241], v[194:197], v[126:129]
	v_mfma_f32_16x16x32_bf16 v[122:125], v[242:245], v[194:197], v[122:125]
	v_mfma_f32_16x16x32_bf16 v[118:121], v[246:249], v[194:197], v[118:121]
	v_mfma_f32_16x16x32_bf16 v[114:117], v[222:225], v[194:197], v[114:117]
	ds_read_b128 v[194:197], v237 offset:4096
	s_waitcnt vmcnt(11)
	ds_write_b128 v234, v[130:133]
	s_waitcnt vmcnt(10)
	ds_write_b128 v234, v[134:137] offset:2048
	buffer_load_dwordx4 v[130:133], v218, s[24:27], 0 offen
	buffer_load_dwordx4 v[134:137], v219, s[24:27], 0 offen
	s_waitcnt lgkmcnt(5)
	v_mfma_f32_16x16x32_bf16 v[110:113], v[238:241], v[198:201], v[110:113]
	v_mfma_f32_16x16x32_bf16 v[106:109], v[242:245], v[198:201], v[106:109]
	v_mfma_f32_16x16x32_bf16 v[102:105], v[246:249], v[198:201], v[102:105]
	v_mfma_f32_16x16x32_bf16 v[98:101], v[222:225], v[198:201], v[98:101]
	ds_read_b128 v[198:201], v237 offset:5120
	s_waitcnt vmcnt(11)
	ds_write_b128 v234, v[138:141] offset:4096
	buffer_load_dwordx4 v[138:141], v218, s[24:27], s27 offen
	s_waitcnt lgkmcnt(6)
	v_mfma_f32_16x16x32_bf16 v[94:97], v[238:241], v[202:205], v[94:97]
	v_mfma_f32_16x16x32_bf16 v[90:93], v[242:245], v[202:205], v[90:93]
	v_mfma_f32_16x16x32_bf16 v[86:89], v[246:249], v[202:205], v[86:89]
	v_mfma_f32_16x16x32_bf16 v[82:85], v[222:225], v[202:205], v[82:85]
	ds_read_b128 v[202:205], v237 offset:6144
	s_waitcnt vmcnt(11)
	ds_write_b128 v234, v[142:145] offset:6144
	s_waitcnt vmcnt(10)
	ds_write_b128 v234, v[146:149] offset:8192
	buffer_load_dwordx4 v[142:145], v219, s[24:27], s27 offen
	buffer_load_dwordx4 v[146:149], v218, s[24:27], s77 offen
	s_waitcnt lgkmcnt(8)
	v_mfma_f32_16x16x32_bf16 v[78:81], v[238:241], v[206:209], v[78:81]
	v_mfma_f32_16x16x32_bf16 v[74:77], v[242:245], v[206:209], v[74:77]
	v_mfma_f32_16x16x32_bf16 v[70:73], v[246:249], v[206:209], v[70:73]
	v_mfma_f32_16x16x32_bf16 v[66:69], v[222:225], v[206:209], v[66:69]
	ds_read_b128 v[206:209], v237 offset:7168
	s_sub_i32 s35, s7, s30
	v_add_u32_e32 v232, s35, v232
	v_add_u32_e32 v237, s35, v237
	s_waitcnt vmcnt(11)
	ds_write_b128 v234, v[150:153] offset:10240
	buffer_load_dwordx4 v[150:153], v219, s[24:27], s77 offen
	s_waitcnt lgkmcnt(9)
	v_mfma_f32_16x16x32_bf16 v[62:65], v[238:241], v[194:197], v[62:65]
	v_mfma_f32_16x16x32_bf16 v[58:61], v[242:245], v[194:197], v[58:61]
	v_mfma_f32_16x16x32_bf16 v[54:57], v[246:249], v[194:197], v[54:57]
	v_mfma_f32_16x16x32_bf16 v[50:53], v[222:225], v[194:197], v[50:53]
	s_waitcnt vmcnt(11)
; template <int MODE>
; __device__ void gemm_tile2(const u16* __restrict__ X, int lda, const u16* __restrict__ W, int ldb, int K,
;                            int m0, int n0, u16* __restrict__ outb, int vbase,
;                            const float* resid, float* outf, unsigned char* smem) {
;     ...
;   G2_GLOAD(0, 0);
;   G2_GLOAD(1, 1);
;   __syncthreads();
;   G2_LSTORE(0, 0);
;   G2_GLOAD(0, 2);
;   __syncthreads();
;   for (int kt2 = 0; kt2 < nk; kt2 += 2) {
; #pragma unroll
;     for (int h = 0; h < 2; ++h) {
;       const int kt = kt2 + h;
;       const u16* st = sbase + h * G2STAGE;
;       bf16x8 fw[4], fx[4];
; #pragma unroll
;       for (int j = 0; j < 4; ++j) fw[j] = *(const bf16x8*)(st + 256 * G2S + (ww * 64 + j * 16 + l15) * G2S + fsw);
; #pragma unroll
;       for (int i = 0; i < 4; ++i) fx[i] = *(const bf16x8*)(st + (wx * 128 + i * 16 + l15) * G2S + fsw);
;       __builtin_amdgcn_sched_barrier(0);
;       __builtin_amdgcn_s_setprio(1);
; #pragma unroll
;       for (int i = 0; i < 4; ++i) {
; #pragma unroll
;         for (int j = 0; j < 4; ++j) {
;           if (MODE == 1) acc[i][j] = mfma16(fx[i], fw[j], acc[i][j]);
;           else acc[i][j] = mfma16(fw[j], fx[i], acc[i][j]);
;         }
;       }
;       __builtin_amdgcn_s_setprio(0);
;       __builtin_amdgcn_sched_barrier(0);
; #pragma unroll
;       for (int i = 0; i < 4; ++i) fx[i] = *(const bf16x8*)(st + (wx * 128 + (i + 4) * 16 + l15) * G2S + fsw);
;       __builtin_amdgcn_sched_barrier(0);
;       if (kt + 1 < nk) G2_LSTORE(1 - h, 1 - h);
;       if (kt + 3 < nk) G2_GLOAD(1 - h, kt + 3);
;       __builtin_amdgcn_sched_barrier(0);
;       __builtin_amdgcn_s_setprio(1);
; #pragma unroll
;       for (int i = 0; i < 4; ++i) {
; #pragma unroll
;         for (int j = 0; j < 4; ++j) {
;           if (MODE == 1) acc[i + 4][j] = mfma16(fx[i], fw[j], acc[i + 4][j]);
;           else acc[i + 4][j] = mfma16(fw[j], fx[i], acc[i + 4][j]);
;         }
;       }
;       __builtin_amdgcn_s_setprio(0);
;       __syncthreads();
;     }
	ds_write_b128 v234, v[154:157] offset:12288
	s_waitcnt vmcnt(10)
	ds_write_b128 v234, v[158:161] offset:14336
	buffer_load_dwordx4 v[154:157], v218, s[24:27], s78 offen
	buffer_load_dwordx4 v[158:161], v219, s[24:27], s78 offen
	s_waitcnt lgkmcnt(8)
	v_mfma_f32_16x16x32_bf16 v[46:49], v[238:241], v[198:201], v[46:49]
	v_mfma_f32_16x16x32_bf16 v[42:45], v[242:245], v[198:201], v[42:45]
	v_mfma_f32_16x16x32_bf16 v[38:41], v[246:249], v[198:201], v[38:41]
	v_mfma_f32_16x16x32_bf16 v[34:37], v[222:225], v[198:201], v[34:37]
	s_waitcnt vmcnt(11)
	ds_write_b128 v234, v[162:165] offset:16384
	buffer_load_dwordx4 v[162:165], v218, s[40:43], 0 offen
	s_waitcnt lgkmcnt(7)
	v_mfma_f32_16x16x32_bf16 v[30:33], v[238:241], v[202:205], v[30:33]
	v_mfma_f32_16x16x32_bf16 v[26:29], v[242:245], v[202:205], v[26:29]
	v_mfma_f32_16x16x32_bf16 v[22:25], v[246:249], v[202:205], v[22:25]
	v_mfma_f32_16x16x32_bf16 v[18:21], v[222:225], v[202:205], v[18:21]
	s_waitcnt vmcnt(11)
	ds_write_b128 v234, v[166:169] offset:18432
	s_waitcnt vmcnt(10)
	ds_write_b128 v234, v[170:173] offset:20480
	buffer_load_dwordx4 v[166:169], v219, s[40:43], 0 offen
	buffer_load_dwordx4 v[170:173], v218, s[40:43], s27 offen
	s_waitcnt lgkmcnt(6)
	v_mfma_f32_16x16x32_bf16 v[14:17], v[238:241], v[206:209], v[14:17]
	v_mfma_f32_16x16x32_bf16 v[10:13], v[242:245], v[206:209], v[10:13]
	v_mfma_f32_16x16x32_bf16 v[6:9], v[246:249], v[206:209], v[6:9]
	v_mfma_f32_16x16x32_bf16 v[2:5], v[222:225], v[206:209], v[2:5]
	s_waitcnt vmcnt(11)
	ds_write_b128 v234, v[174:177] offset:22528
	buffer_load_dwordx4 v[174:177], v219, s[40:43], s27 offen
	v_add_u32_e32 v218, 0x80, v218
	v_add_u32_e32 v219, 0x80, v219
	s_waitcnt lgkmcnt(0)
	s_setprio 0
	s_barrier
	s_mov_b32 s35, s31
	s_mov_b32 s31, s30
	s_mov_b32 s30, s7
	s_mov_b32 s7, s35
	ds_read_b128 v[178:181], v235 offset:16384
	ds_read_b128 v[182:185], v235 offset:17408
	ds_read_b128 v[186:189], v235 offset:18432
	ds_read_b128 v[190:193], v235 offset:19456
	ds_read_b128 v[194:197], v236
	ds_read_b128 v[198:201], v236 offset:1024
	ds_read_b128 v[202:205], v236 offset:2048
	ds_read_b128 v[206:209], v236 offset:3072
	s_add_u32 s6, s6, 1
	s_cmp_lt_u32 s6, 14
	s_cbranch_scc1 .Lf2_loop
	s_waitcnt lgkmcnt(3)
	v_mfma_f32_16x16x32_bf16 v[126:129], v[178:181], v[194:197], v[126:129]
	v_mfma_f32_16x16x32_bf16 v[122:125], v[182:185], v[194:197], v[122:125]
	v_mfma_f32_16x16x32_bf16 v[118:121], v[186:189], v[194:197], v[118:121]
	v_mfma_f32_16x16x32_bf16 v[114:117], v[190:193], v[194:197], v[114:117]
	ds_read_b128 v[194:197], v236 offset:4096
	ds_read_b128 v[238:241], v232 offset:16384
	s_waitcnt lgkmcnt(4)
	v_mfma_f32_16x16x32_bf16 v[110:113], v[178:181], v[198:201], v[110:113]
	v_mfma_f32_16x16x32_bf16 v[106:109], v[182:185], v[198:201], v[106:109]
	v_mfma_f32_16x16x32_bf16 v[102:105], v[186:189], v[198:201], v[102:105]
	v_mfma_f32_16x16x32_bf16 v[98:101], v[190:193], v[198:201], v[98:101]
	ds_read_b128 v[198:201], v236 offset:5120
	ds_read_b128 v[242:245], v232 offset:17408
	s_waitcnt lgkmcnt(5)
	v_mfma_f32_16x16x32_bf16 v[94:97], v[178:181], v[202:205], v[94:97]
	v_mfma_f32_16x16x32_bf16 v[90:93], v[182:185], v[202:205], v[90:93]
	v_mfma_f32_16x16x32_bf16 v[86:89], v[186:189], v[202:205], v[86:89]
	v_mfma_f32_16x16x32_bf16 v[82:85], v[190:193], v[202:205], v[82:85]
	ds_read_b128 v[202:205], v236 offset:6144
	ds_read_b128 v[246:249], v232 offset:18432
	s_waitcnt lgkmcnt(6)
	v_mfma_f32_16x16x32_bf16 v[78:81], v[178:181], v[206:209], v[78:81]
	v_mfma_f32_16x16x32_bf16 v[74:77], v[182:185], v[206:209], v[74:77]
	v_mfma_f32_16x16x32_bf16 v[70:73], v[186:189], v[206:209], v[70:73]
	v_mfma_f32_16x16x32_bf16 v[66:69], v[190:193], v[206:209], v[66:69]
	ds_read_b128 v[206:209], v236 offset:7168
	ds_read_b128 v[222:225], v232 offset:19456
	s_sub_i32 s35, s31, s7
	v_add_u32_e32 v235, s35, v235
	v_add_u32_e32 v236, s35, v236
	s_waitcnt lgkmcnt(7)
	v_mfma_f32_16x16x32_bf16 v[62:65], v[178:181], v[194:197], v[62:65]
	v_mfma_f32_16x16x32_bf16 v[58:61], v[182:185], v[194:197], v[58:61]
	v_mfma_f32_16x16x32_bf16 v[54:57], v[186:189], v[194:197], v[54:57]
	v_mfma_f32_16x16x32_bf16 v[50:53], v[190:193], v[194:197], v[50:53]
	ds_read_b128 v[194:197], v237
	s_waitcnt lgkmcnt(6)
	v_mfma_f32_16x16x32_bf16 v[46:49], v[178:181], v[198:201], v[46:49]
	v_mfma_f32_16x16x32_bf16 v[42:45], v[182:185], v[198:201], v[42:45]
	v_mfma_f32_16x16x32_bf16 v[38:41], v[186:189], v[198:201], v[38:41]
	v_mfma_f32_16x16x32_bf16 v[34:37], v[190:193], v[198:201], v[34:37]
	ds_read_b128 v[198:201], v237 offset:1024
	s_waitcnt lgkmcnt(5)
	v_mfma_f32_16x16x32_bf16 v[30:33], v[178:181], v[202:205], v[30:33]
	v_mfma_f32_16x16x32_bf16 v[26:29], v[182:185], v[202:205], v[26:29]
	v_mfma_f32_16x16x32_bf16 v[22:25], v[186:189], v[202:205], v[22:25]
	v_mfma_f32_16x16x32_bf16 v[18:21], v[190:193], v[202:205], v[18:21]
	ds_read_b128 v[202:205], v237 offset:2048
	s_waitcnt lgkmcnt(4)
	v_mfma_f32_16x16x32_bf16 v[14:17], v[178:181], v[206:209], v[14:17]
	v_mfma_f32_16x16x32_bf16 v[10:13], v[182:185], v[206:209], v[10:13]
	v_mfma_f32_16x16x32_bf16 v[6:9], v[186:189], v[206:209], v[6:9]
	v_mfma_f32_16x16x32_bf16 v[2:5], v[190:193], v[206:209], v[2:5]
	ds_read_b128 v[206:209], v237 offset:3072
	s_sub_i32 s35, s7, s31
	v_mad_i32_i24 v234, v221, s35, v220
	v_add_u32_e32 v234, s31, v234
	s_barrier
; template <int MODE>
; __device__ void gemm_tile2(const u16* __restrict__ X, int lda, const u16* __restrict__ W, int ldb, int K,
;                            int m0, int n0, u16* __restrict__ outb, int vbase,
;                            const float* resid, float* outf, unsigned char* smem) {
;     ...
; #pragma unroll
;       for (int i = 0; i < 4; ++i) fx[i] = *(const bf16x8*)(st + (wx * 128 + (i + 4) * 16 + l15) * G2S + fsw);
;       __builtin_amdgcn_sched_barrier(0);
;       if (kt + 1 < nk) G2_LSTORE(1 - h, 1 - h);
;       if (kt + 3 < nk) G2_GLOAD(1 - h, kt + 3);
;       __builtin_amdgcn_sched_barrier(0);
;       __builtin_amdgcn_s_setprio(1);
; #pragma unroll
;       for (int i = 0; i < 4; ++i) {
; #pragma unroll
;         for (int j = 0; j < 4; ++j) {
;           if (MODE == 1) acc[i + 4][j] = mfma16(fx[i], fw[j], acc[i + 4][j]);
;           else acc[i + 4][j] = mfma16(fw[j], fx[i], acc[i + 4][j]);
;         }
;       }
;       __builtin_amdgcn_s_setprio(0);
;       __syncthreads();
	s_setprio 1
	s_waitcnt lgkmcnt(3)
	v_mfma_f32_16x16x32_bf16 v[126:129], v[238:241], v[194:197], v[126:129]
	v_mfma_f32_16x16x32_bf16 v[122:125], v[242:245], v[194:197], v[122:125]
	v_mfma_f32_16x16x32_bf16 v[118:121], v[246:249], v[194:197], v[118:121]
	v_mfma_f32_16x16x32_bf16 v[114:117], v[222:225], v[194:197], v[114:117]
	ds_read_b128 v[194:197], v237 offset:4096
	s_waitcnt vmcnt(11)
	ds_write_b128 v234, v[130:133]
	s_waitcnt vmcnt(10)
	ds_write_b128 v234, v[134:137] offset:2048
	s_waitcnt lgkmcnt(5)
	v_mfma_f32_16x16x32_bf16 v[110:113], v[238:241], v[198:201], v[110:113]
	v_mfma_f32_16x16x32_bf16 v[106:109], v[242:245], v[198:201], v[106:109]
	v_mfma_f32_16x16x32_bf16 v[102:105], v[246:249], v[198:201], v[102:105]
	v_mfma_f32_16x16x32_bf16 v[98:101], v[222:225], v[198:201], v[98:101]
	ds_read_b128 v[198:201], v237 offset:5120
	s_waitcnt vmcnt(9)
	ds_write_b128 v234, v[138:141] offset:4096
	s_waitcnt lgkmcnt(6)
	v_mfma_f32_16x16x32_bf16 v[94:97], v[238:241], v[202:205], v[94:97]
	v_mfma_f32_16x16x32_bf16 v[90:93], v[242:245], v[202:205], v[90:93]
	v_mfma_f32_16x16x32_bf16 v[86:89], v[246:249], v[202:205], v[86:89]
	v_mfma_f32_16x16x32_bf16 v[82:85], v[222:225], v[202:205], v[82:85]
	ds_read_b128 v[202:205], v237 offset:6144
	s_waitcnt vmcnt(8)
	ds_write_b128 v234, v[142:145] offset:6144
	s_waitcnt vmcnt(7)
	ds_write_b128 v234, v[146:149] offset:8192
	s_waitcnt lgkmcnt(8)
	v_mfma_f32_16x16x32_bf16 v[78:81], v[238:241], v[206:209], v[78:81]
	v_mfma_f32_16x16x32_bf16 v[74:77], v[242:245], v[206:209], v[74:77]
	v_mfma_f32_16x16x32_bf16 v[70:73], v[246:249], v[206:209], v[70:73]
	v_mfma_f32_16x16x32_bf16 v[66:69], v[222:225], v[206:209], v[66:69]
	ds_read_b128 v[206:209], v237 offset:7168
	s_sub_i32 s35, s7, s30
	v_add_u32_e32 v232, s35, v232
	v_add_u32_e32 v237, s35, v237
	s_waitcnt vmcnt(6)
	ds_write_b128 v234, v[150:153] offset:10240
	s_waitcnt lgkmcnt(9)
	v_mfma_f32_16x16x32_bf16 v[62:65], v[238:241], v[194:197], v[62:65]
	v_mfma_f32_16x16x32_bf16 v[58:61], v[242:245], v[194:197], v[58:61]
	v_mfma_f32_16x16x32_bf16 v[54:57], v[246:249], v[194:197], v[54:57]
	v_mfma_f32_16x16x32_bf16 v[50:53], v[222:225], v[194:197], v[50:53]
	s_waitcnt vmcnt(5)
	ds_write_b128 v234, v[154:157] offset:12288
	s_waitcnt vmcnt(4)
	ds_write_b128 v234, v[158:161] offset:14336
	s_waitcnt lgkmcnt(8)
	v_mfma_f32_16x16x32_bf16 v[46:49], v[238:241], v[198:201], v[46:49]
	v_mfma_f32_16x16x32_bf16 v[42:45], v[242:245], v[198:201], v[42:45]
	v_mfma_f32_16x16x32_bf16 v[38:41], v[246:249], v[198:201], v[38:41]
	v_mfma_f32_16x16x32_bf16 v[34:37], v[222:225], v[198:201], v[34:37]
	s_waitcnt vmcnt(3)
	ds_write_b128 v234, v[162:165] offset:16384
	s_waitcnt lgkmcnt(7)
	v_mfma_f32_16x16x32_bf16 v[30:33], v[238:241], v[202:205], v[30:33]
	v_mfma_f32_16x16x32_bf16 v[26:29], v[242:245], v[202:205], v[26:29]
	v_mfma_f32_16x16x32_bf16 v[22:25], v[246:249], v[202:205], v[22:25]
	v_mfma_f32_16x16x32_bf16 v[18:21], v[222:225], v[202:205], v[18:21]
	s_waitcnt vmcnt(2)
	ds_write_b128 v234, v[166:169] offset:18432
	s_waitcnt vmcnt(1)
	ds_write_b128 v234, v[170:173] offset:20480
	s_waitcnt lgkmcnt(6)
	v_mfma_f32_16x16x32_bf16 v[14:17], v[238:241], v[206:209], v[14:17]
	v_mfma_f32_16x16x32_bf16 v[10:13], v[242:245], v[206:209], v[10:13]
	v_mfma_f32_16x16x32_bf16 v[6:9], v[246:249], v[206:209], v[6:9]
	v_mfma_f32_16x16x32_bf16 v[2:5], v[222:225], v[206:209], v[2:5]
	s_waitcnt vmcnt(0)
	ds_write_b128 v234, v[174:177] offset:22528
	s_waitcnt lgkmcnt(0)
	s_setprio 0
	s_barrier
; template <int MODE>
; __device__ void gemm_tile2(const u16* __restrict__ X, int lda, const u16* __restrict__ W, int ldb, int K,
;                            int m0, int n0, u16* __restrict__ outb, int vbase,
;                            const float* resid, float* outf, unsigned char* smem) {
;     ...
;   for (int kt2 = 0; kt2 < nk; kt2 += 2) {
; #pragma unroll
;     for (int h = 0; h < 2; ++h) {
;       const int kt = kt2 + h;
;       const u16* st = sbase + h * G2STAGE;
;       bf16x8 fw[4], fx[4];
; #pragma unroll
;       for (int j = 0; j < 4; ++j) fw[j] = *(const bf16x8*)(st + 256 * G2S + (ww * 64 + j * 16 + l15) * G2S + fsw);
; #pragma unroll
;       for (int i = 0; i < 4; ++i) fx[i] = *(const bf16x8*)(st + (wx * 128 + i * 16 + l15) * G2S + fsw);
;       __builtin_amdgcn_sched_barrier(0);
;       __builtin_amdgcn_s_setprio(1);
; #pragma unroll
;       for (int i = 0; i < 4; ++i) {
; #pragma unroll
;         for (int j = 0; j < 4; ++j) {
;           if (MODE == 1) acc[i][j] = mfma16(fx[i], fw[j], acc[i][j]);
;           else acc[i][j] = mfma16(fw[j], fx[i], acc[i][j]);
;         }
;       }
;       __builtin_amdgcn_s_setprio(0);
;       __builtin_amdgcn_sched_barrier(0);
; #pragma unroll
;       for (int i = 0; i < 4; ++i) fx[i] = *(const bf16x8*)(st + (wx * 128 + (i + 4) * 16 + l15) * G2S + fsw);
;       __builtin_amdgcn_sched_barrier(0);
;       if (kt + 1 < nk) G2_LSTORE(1 - h, 1 - h);
;       if (kt + 3 < nk) G2_GLOAD(1 - h, kt + 3);
;       __builtin_amdgcn_sched_barrier(0);
;       __builtin_amdgcn_s_setprio(1);
; #pragma unroll
;       for (int i = 0; i < 4; ++i) {
; #pragma unroll
;         for (int j = 0; j < 4; ++j) {
;           if (MODE == 1) acc[i + 4][j] = mfma16(fx[i], fw[j], acc[i + 4][j]);
;           else acc[i + 4][j] = mfma16(fw[j], fx[i], acc[i + 4][j]);
;         }
;       }
;       __builtin_amdgcn_s_setprio(0);
;       __syncthreads();
;     }
;   }
	s_mov_b32 s35, s31
	s_mov_b32 s31, s30
	s_mov_b32 s30, s7
	s_mov_b32 s7, s35
	ds_read_b128 v[178:181], v235 offset:16384
	ds_read_b128 v[182:185], v235 offset:17408
	ds_read_b128 v[186:189], v235 offset:18432
	ds_read_b128 v[190:193], v235 offset:19456
	ds_read_b128 v[194:197], v236
	ds_read_b128 v[198:201], v236 offset:1024
	ds_read_b128 v[202:205], v236 offset:2048
	ds_read_b128 v[206:209], v236 offset:3072
	s_waitcnt lgkmcnt(3)
	v_mfma_f32_16x16x32_bf16 v[126:129], v[178:181], v[194:197], v[126:129]
	v_mfma_f32_16x16x32_bf16 v[122:125], v[182:185], v[194:197], v[122:125]
	v_mfma_f32_16x16x32_bf16 v[118:121], v[186:189], v[194:197], v[118:121]
	v_mfma_f32_16x16x32_bf16 v[114:117], v[190:193], v[194:197], v[114:117]
	ds_read_b128 v[194:197], v236 offset:4096
	ds_read_b128 v[238:241], v232 offset:16384
	s_waitcnt lgkmcnt(4)
	v_mfma_f32_16x16x32_bf16 v[110:113], v[178:181], v[198:201], v[110:113]
	v_mfma_f32_16x16x32_bf16 v[106:109], v[182:185], v[198:201], v[106:109]
	v_mfma_f32_16x16x32_bf16 v[102:105], v[186:189], v[198:201], v[102:105]
	v_mfma_f32_16x16x32_bf16 v[98:101], v[190:193], v[198:201], v[98:101]
	ds_read_b128 v[198:201], v236 offset:5120
	ds_read_b128 v[242:245], v232 offset:17408
	s_waitcnt lgkmcnt(5)
	v_mfma_f32_16x16x32_bf16 v[94:97], v[178:181], v[202:205], v[94:97]
	v_mfma_f32_16x16x32_bf16 v[90:93], v[182:185], v[202:205], v[90:93]
	v_mfma_f32_16x16x32_bf16 v[86:89], v[186:189], v[202:205], v[86:89]
	v_mfma_f32_16x16x32_bf16 v[82:85], v[190:193], v[202:205], v[82:85]
	ds_read_b128 v[202:205], v236 offset:6144
	ds_read_b128 v[246:249], v232 offset:18432
	s_waitcnt lgkmcnt(6)
	v_mfma_f32_16x16x32_bf16 v[78:81], v[178:181], v[206:209], v[78:81]
	v_mfma_f32_16x16x32_bf16 v[74:77], v[182:185], v[206:209], v[74:77]
	v_mfma_f32_16x16x32_bf16 v[70:73], v[186:189], v[206:209], v[70:73]
	v_mfma_f32_16x16x32_bf16 v[66:69], v[190:193], v[206:209], v[66:69]
	ds_read_b128 v[206:209], v236 offset:7168
	ds_read_b128 v[222:225], v232 offset:19456
	s_sub_i32 s35, s31, s7
	v_add_u32_e32 v235, s35, v235
	v_add_u32_e32 v236, s35, v236
	s_waitcnt lgkmcnt(7)
	v_mfma_f32_16x16x32_bf16 v[62:65], v[178:181], v[194:197], v[62:65]
	v_mfma_f32_16x16x32_bf16 v[58:61], v[182:185], v[194:197], v[58:61]
	v_mfma_f32_16x16x32_bf16 v[54:57], v[186:189], v[194:197], v[54:57]
	v_mfma_f32_16x16x32_bf16 v[50:53], v[190:193], v[194:197], v[50:53]
	ds_read_b128 v[194:197], v237
	s_waitcnt lgkmcnt(6)
	v_mfma_f32_16x16x32_bf16 v[46:49], v[178:181], v[198:201], v[46:49]
	v_mfma_f32_16x16x32_bf16 v[42:45], v[182:185], v[198:201], v[42:45]
	v_mfma_f32_16x16x32_bf16 v[38:41], v[186:189], v[198:201], v[38:41]
	v_mfma_f32_16x16x32_bf16 v[34:37], v[190:193], v[198:201], v[34:37]
	ds_read_b128 v[198:201], v237 offset:1024
	s_waitcnt lgkmcnt(5)
	v_mfma_f32_16x16x32_bf16 v[30:33], v[178:181], v[202:205], v[30:33]
	v_mfma_f32_16x16x32_bf16 v[26:29], v[182:185], v[202:205], v[26:29]
	v_mfma_f32_16x16x32_bf16 v[22:25], v[186:189], v[202:205], v[22:25]
	v_mfma_f32_16x16x32_bf16 v[18:21], v[190:193], v[202:205], v[18:21]
	ds_read_b128 v[202:205], v237 offset:2048
	s_waitcnt lgkmcnt(4)
	v_mfma_f32_16x16x32_bf16 v[14:17], v[178:181], v[206:209], v[14:17]
	v_mfma_f32_16x16x32_bf16 v[10:13], v[182:185], v[206:209], v[10:13]
	v_mfma_f32_16x16x32_bf16 v[6:9], v[186:189], v[206:209], v[6:9]
	v_mfma_f32_16x16x32_bf16 v[2:5], v[190:193], v[206:209], v[2:5]
	ds_read_b128 v[206:209], v237 offset:3072
	s_barrier
	s_setprio 1
	s_waitcnt lgkmcnt(3)
	v_mfma_f32_16x16x32_bf16 v[126:129], v[238:241], v[194:197], v[126:129]
	v_mfma_f32_16x16x32_bf16 v[122:125], v[242:245], v[194:197], v[122:125]
	v_mfma_f32_16x16x32_bf16 v[118:121], v[246:249], v[194:197], v[118:121]
	v_mfma_f32_16x16x32_bf16 v[114:117], v[222:225], v[194:197], v[114:117]
	ds_read_b128 v[194:197], v237 offset:4096
	s_waitcnt lgkmcnt(3)
	v_mfma_f32_16x16x32_bf16 v[110:113], v[238:241], v[198:201], v[110:113]
	v_mfma_f32_16x16x32_bf16 v[106:109], v[242:245], v[198:201], v[106:109]
	v_mfma_f32_16x16x32_bf16 v[102:105], v[246:249], v[198:201], v[102:105]
	v_mfma_f32_16x16x32_bf16 v[98:101], v[222:225], v[198:201], v[98:101]
	ds_read_b128 v[198:201], v237 offset:5120
	s_waitcnt lgkmcnt(3)
	v_mfma_f32_16x16x32_bf16 v[94:97], v[238:241], v[202:205], v[94:97]
	v_mfma_f32_16x16x32_bf16 v[90:93], v[242:245], v[202:205], v[90:93]
	v_mfma_f32_16x16x32_bf16 v[86:89], v[246:249], v[202:205], v[86:89]
	v_mfma_f32_16x16x32_bf16 v[82:85], v[222:225], v[202:205], v[82:85]
	ds_read_b128 v[202:205], v237 offset:6144
	s_waitcnt lgkmcnt(3)
	v_mfma_f32_16x16x32_bf16 v[78:81], v[238:241], v[206:209], v[78:81]
	v_mfma_f32_16x16x32_bf16 v[74:77], v[242:245], v[206:209], v[74:77]
	v_mfma_f32_16x16x32_bf16 v[70:73], v[246:249], v[206:209], v[70:73]
	v_mfma_f32_16x16x32_bf16 v[66:69], v[222:225], v[206:209], v[66:69]
	ds_read_b128 v[206:209], v237 offset:7168
	s_sub_i32 s35, s7, s30
	v_add_u32_e32 v232, s35, v232
	v_add_u32_e32 v237, s35, v237
	s_waitcnt lgkmcnt(3)
	v_mfma_f32_16x16x32_bf16 v[62:65], v[238:241], v[194:197], v[62:65]
	v_mfma_f32_16x16x32_bf16 v[58:61], v[242:245], v[194:197], v[58:61]
	v_mfma_f32_16x16x32_bf16 v[54:57], v[246:249], v[194:197], v[54:57]
	v_mfma_f32_16x16x32_bf16 v[50:53], v[222:225], v[194:197], v[50:53]
	s_waitcnt lgkmcnt(2)
	v_mfma_f32_16x16x32_bf16 v[46:49], v[238:241], v[198:201], v[46:49]
	v_mfma_f32_16x16x32_bf16 v[42:45], v[242:245], v[198:201], v[42:45]
	v_mfma_f32_16x16x32_bf16 v[38:41], v[246:249], v[198:201], v[38:41]
	v_mfma_f32_16x16x32_bf16 v[34:37], v[222:225], v[198:201], v[34:37]
	s_waitcnt lgkmcnt(1)
	v_mfma_f32_16x16x32_bf16 v[30:33], v[238:241], v[202:205], v[30:33]
	v_mfma_f32_16x16x32_bf16 v[26:29], v[242:245], v[202:205], v[26:29]
	v_mfma_f32_16x16x32_bf16 v[22:25], v[246:249], v[202:205], v[22:25]
	v_mfma_f32_16x16x32_bf16 v[18:21], v[222:225], v[202:205], v[18:21]
	s_waitcnt lgkmcnt(0)
	v_mfma_f32_16x16x32_bf16 v[14:17], v[238:241], v[206:209], v[14:17]
	v_mfma_f32_16x16x32_bf16 v[10:13], v[242:245], v[206:209], v[10:13]
	v_mfma_f32_16x16x32_bf16 v[6:9], v[246:249], v[206:209], v[6:9]
	v_mfma_f32_16x16x32_bf16 v[2:5], v[222:225], v[206:209], v[2:5]
	s_setprio 0
	s_barrier
	s_mov_b32 s35, s31
	s_mov_b32 s31, s30
	s_mov_b32 s30, s7
	s_mov_b32 s7, s35
	s_nop 7
